# P2: de-serialised hand-written LayerNorm passes for both the sample-group item (b) and the prompt-group rows (c): all row loads issued up front, one wait chain each
# speedup vs baseline: 1.0045x; 1.0045x over previous
.LBB0_345:
	s_and_b32 s6, s25, 3
	s_lshl_b32 s29, s6, 8
	v_or_b32_e32 v0, s29, v105
	v_lshlrev_b32_e32 v12, 2, v0
	s_waitcnt lgkmcnt(0)
	global_load_dwordx4 v[0:3], v12, s[44:45]
	global_load_dwordx4 v[4:7], v12, s[44:45] offset:16
	global_load_dwordx4 v[8:11], v12, s[46:47]
	s_nop 0
	global_load_dwordx4 v[12:15], v12, s[46:47] offset:16
	s_ashr_i32 s54, s25, 2
	s_and_b32 s4, s25, 1
	s_lshl_b32 s8, s54, 7
	s_cmp_lt_u32 s6, 2
	s_cselect_b64 s[6:7], -1, 0
	s_add_i32 s8, s3, s8
	v_cmp_eq_u32_e64 s[4:5], s4, v104
	v_mad_i64_i32 v[36:37], s[8:9], s8, v108, v[34:35]
	s_mov_b32 s49, -4
	v_mov_b32_e32 v109, v107
	s_cmpk_lg_i32 s26, 0x100
	s_cbranch_scc1 .LBB0_347
	s_movk_i32 s10, 0x4800
	s_mov_b32 s11, 0
	v_and_b32_e32 v240, 63, v164
	v_lshlrev_b32_e32 v228, 2, v240
	v_mov_b32_e32 v230, v36
	v_mov_b32_e32 v231, v37
	global_load_dwordx4 v[16:19], v[230:231], off
	global_load_dwordx4 v[20:23], v[230:231], off offset:1024
	v_lshl_add_u64 v[230:231], v[230:231], 0, s[10:11]
	global_load_dwordx4 v[24:27], v[230:231], off
	global_load_dwordx4 v[28:31], v[230:231], off offset:1024
	v_lshl_add_u64 v[230:231], v[230:231], 0, s[10:11]
	global_load_dwordx4 v[36:39], v[230:231], off
	global_load_dwordx4 v[40:43], v[230:231], off offset:1024
	v_lshl_add_u64 v[230:231], v[230:231], 0, s[10:11]
	global_load_dwordx4 v[44:47], v[230:231], off
	global_load_dwordx4 v[48:51], v[230:231], off offset:1024
	v_lshl_add_u64 v[230:231], v[230:231], 0, s[10:11]
	global_load_dwordx4 v[52:55], v[230:231], off
	global_load_dwordx4 v[56:59], v[230:231], off offset:1024
	v_lshl_add_u64 v[230:231], v[230:231], 0, s[10:11]
	global_load_dwordx4 v[60:63], v[230:231], off
	global_load_dwordx4 v[64:67], v[230:231], off offset:1024
	v_lshl_add_u64 v[230:231], v[230:231], 0, s[10:11]
	global_load_dwordx4 v[68:71], v[230:231], off
	global_load_dwordx4 v[72:75], v[230:231], off offset:1024
	v_lshl_add_u64 v[230:231], v[230:231], 0, s[10:11]
	global_load_dwordx4 v[76:79], v[230:231], off
	global_load_dwordx4 v[80:83], v[230:231], off offset:1024
	v_lshl_add_u64 v[230:231], v[230:231], 0, s[10:11]
	global_load_dwordx4 v[84:87], v[230:231], off
	global_load_dwordx4 v[88:91], v[230:231], off offset:1024
	v_lshl_add_u64 v[230:231], v[230:231], 0, s[10:11]
	global_load_dwordx4 v[92:95], v[230:231], off
	global_load_dwordx4 v[110:113], v[230:231], off offset:1024
	v_lshl_add_u64 v[230:231], v[230:231], 0, s[10:11]
	global_load_dwordx4 v[114:117], v[230:231], off
	global_load_dwordx4 v[118:121], v[230:231], off offset:1024
	v_lshl_add_u64 v[230:231], v[230:231], 0, s[10:11]
	global_load_dwordx4 v[122:125], v[230:231], off
	global_load_dwordx4 v[148:151], v[230:231], off offset:1024
	v_lshl_add_u64 v[230:231], v[230:231], 0, s[10:11]
	global_load_dwordx4 v[152:155], v[230:231], off
	global_load_dwordx4 v[156:159], v[230:231], off offset:1024
	v_lshl_add_u64 v[230:231], v[230:231], 0, s[10:11]
	global_load_dwordx4 v[160:163], v[230:231], off
	global_load_dwordx4 v[166:169], v[230:231], off offset:1024
	v_lshl_add_u64 v[230:231], v[230:231], 0, s[10:11]
	global_load_dwordx4 v[170:173], v[230:231], off
	global_load_dwordx4 v[174:177], v[230:231], off offset:1024
	v_lshl_add_u64 v[230:231], v[230:231], 0, s[10:11]
	global_load_dwordx4 v[178:181], v[230:231], off
	global_load_dwordx4 v[182:185], v[230:231], off offset:1024
	s_waitcnt vmcnt(16)
	v_mov_b32_e32 v186, 0
	v_lshlrev_b32_e32 v218, 16, v16
	v_lshlrev_b32_e32 v219, 16, v20
	v_add_f32_e32 v218, v218, v219
	v_add_f32_e32 v186, v186, v218
	v_and_b32_e32 v220, 0xffff0000, v16
	v_and_b32_e32 v221, 0xffff0000, v20
	v_add_f32_e32 v220, v220, v221
	v_add_f32_e32 v186, v186, v220
	v_lshlrev_b32_e32 v218, 16, v17
	v_lshlrev_b32_e32 v219, 16, v21
	v_add_f32_e32 v218, v218, v219
	v_add_f32_e32 v186, v186, v218
	v_and_b32_e32 v220, 0xffff0000, v17
	v_and_b32_e32 v221, 0xffff0000, v21
	v_add_f32_e32 v220, v220, v221
	v_add_f32_e32 v186, v186, v220
	v_lshlrev_b32_e32 v218, 16, v18
	v_lshlrev_b32_e32 v219, 16, v22
	v_add_f32_e32 v218, v218, v219
	v_add_f32_e32 v186, v186, v218
	v_and_b32_e32 v220, 0xffff0000, v18
	v_and_b32_e32 v221, 0xffff0000, v22
	v_add_f32_e32 v220, v220, v221
	v_add_f32_e32 v186, v186, v220
	v_lshlrev_b32_e32 v218, 16, v19
	v_lshlrev_b32_e32 v219, 16, v23
	v_add_f32_e32 v218, v218, v219
	v_add_f32_e32 v186, v186, v218
	v_and_b32_e32 v220, 0xffff0000, v19
	v_and_b32_e32 v221, 0xffff0000, v23
	v_add_f32_e32 v220, v220, v221
	v_add_f32_e32 v186, v186, v220
	v_mov_b32_e32 v187, 0
	v_lshlrev_b32_e32 v218, 16, v24
	v_lshlrev_b32_e32 v219, 16, v28
	v_add_f32_e32 v218, v218, v219
	v_add_f32_e32 v187, v187, v218
	v_and_b32_e32 v220, 0xffff0000, v24
	v_and_b32_e32 v221, 0xffff0000, v28
	v_add_f32_e32 v220, v220, v221
	v_add_f32_e32 v187, v187, v220
	v_lshlrev_b32_e32 v218, 16, v25
	v_lshlrev_b32_e32 v219, 16, v29
	v_add_f32_e32 v218, v218, v219
	v_add_f32_e32 v187, v187, v218
	v_and_b32_e32 v220, 0xffff0000, v25
	v_and_b32_e32 v221, 0xffff0000, v29
	v_add_f32_e32 v220, v220, v221
	v_add_f32_e32 v187, v187, v220
	v_lshlrev_b32_e32 v218, 16, v26
	v_lshlrev_b32_e32 v219, 16, v30
	v_add_f32_e32 v218, v218, v219
	v_add_f32_e32 v187, v187, v218
	v_and_b32_e32 v220, 0xffff0000, v26
	v_and_b32_e32 v221, 0xffff0000, v30
	v_add_f32_e32 v220, v220, v221
	v_add_f32_e32 v187, v187, v220
	v_lshlrev_b32_e32 v218, 16, v27
	v_lshlrev_b32_e32 v219, 16, v31
	v_add_f32_e32 v218, v218, v219
	v_add_f32_e32 v187, v187, v218
	v_and_b32_e32 v220, 0xffff0000, v27
	v_and_b32_e32 v221, 0xffff0000, v31
	v_add_f32_e32 v220, v220, v221
	v_add_f32_e32 v187, v187, v220
	v_mov_b32_e32 v188, 0
	v_lshlrev_b32_e32 v218, 16, v36
	v_lshlrev_b32_e32 v219, 16, v40
	v_add_f32_e32 v218, v218, v219
	v_add_f32_e32 v188, v188, v218
	v_and_b32_e32 v220, 0xffff0000, v36
	v_and_b32_e32 v221, 0xffff0000, v40
	v_add_f32_e32 v220, v220, v221
	v_add_f32_e32 v188, v188, v220
	v_lshlrev_b32_e32 v218, 16, v37
	v_lshlrev_b32_e32 v219, 16, v41
	v_add_f32_e32 v218, v218, v219
	v_add_f32_e32 v188, v188, v218
	v_and_b32_e32 v220, 0xffff0000, v37
	v_and_b32_e32 v221, 0xffff0000, v41
	v_add_f32_e32 v220, v220, v221
	v_add_f32_e32 v188, v188, v220
	v_lshlrev_b32_e32 v218, 16, v38
	v_lshlrev_b32_e32 v219, 16, v42
	v_add_f32_e32 v218, v218, v219
	v_add_f32_e32 v188, v188, v218
	v_and_b32_e32 v220, 0xffff0000, v38
	v_and_b32_e32 v221, 0xffff0000, v42
	v_add_f32_e32 v220, v220, v221
	v_add_f32_e32 v188, v188, v220
	v_lshlrev_b32_e32 v218, 16, v39
	v_lshlrev_b32_e32 v219, 16, v43
	v_add_f32_e32 v218, v218, v219
	v_add_f32_e32 v188, v188, v218
	v_and_b32_e32 v220, 0xffff0000, v39
	v_and_b32_e32 v221, 0xffff0000, v43
	v_add_f32_e32 v220, v220, v221
	v_add_f32_e32 v188, v188, v220
	v_mov_b32_e32 v189, 0
	v_lshlrev_b32_e32 v218, 16, v44
	v_lshlrev_b32_e32 v219, 16, v48
	v_add_f32_e32 v218, v218, v219
	v_add_f32_e32 v189, v189, v218
	v_and_b32_e32 v220, 0xffff0000, v44
	v_and_b32_e32 v221, 0xffff0000, v48
	v_add_f32_e32 v220, v220, v221
	v_add_f32_e32 v189, v189, v220
	v_lshlrev_b32_e32 v218, 16, v45
	v_lshlrev_b32_e32 v219, 16, v49
	v_add_f32_e32 v218, v218, v219
	v_add_f32_e32 v189, v189, v218
	v_and_b32_e32 v220, 0xffff0000, v45
	v_and_b32_e32 v221, 0xffff0000, v49
	v_add_f32_e32 v220, v220, v221
	v_add_f32_e32 v189, v189, v220
	v_lshlrev_b32_e32 v218, 16, v46
	v_lshlrev_b32_e32 v219, 16, v50
	v_add_f32_e32 v218, v218, v219
	v_add_f32_e32 v189, v189, v218
	v_and_b32_e32 v220, 0xffff0000, v46
	v_and_b32_e32 v221, 0xffff0000, v50
	v_add_f32_e32 v220, v220, v221
	v_add_f32_e32 v189, v189, v220
	v_lshlrev_b32_e32 v218, 16, v47
	v_lshlrev_b32_e32 v219, 16, v51
	v_add_f32_e32 v218, v218, v219
	v_add_f32_e32 v189, v189, v218
	v_and_b32_e32 v220, 0xffff0000, v47
	v_and_b32_e32 v221, 0xffff0000, v51
	v_add_f32_e32 v220, v220, v221
	v_add_f32_e32 v189, v189, v220
	v_mov_b32_e32 v190, 0
	v_lshlrev_b32_e32 v218, 16, v52
	v_lshlrev_b32_e32 v219, 16, v56
	v_add_f32_e32 v218, v218, v219
	v_add_f32_e32 v190, v190, v218
	v_and_b32_e32 v220, 0xffff0000, v52
	v_and_b32_e32 v221, 0xffff0000, v56
	v_add_f32_e32 v220, v220, v221
	v_add_f32_e32 v190, v190, v220
	v_lshlrev_b32_e32 v218, 16, v53
	v_lshlrev_b32_e32 v219, 16, v57
	v_add_f32_e32 v218, v218, v219
	v_add_f32_e32 v190, v190, v218
	v_and_b32_e32 v220, 0xffff0000, v53
	v_and_b32_e32 v221, 0xffff0000, v57
	v_add_f32_e32 v220, v220, v221
	v_add_f32_e32 v190, v190, v220
	v_lshlrev_b32_e32 v218, 16, v54
	v_lshlrev_b32_e32 v219, 16, v58
	v_add_f32_e32 v218, v218, v219
	v_add_f32_e32 v190, v190, v218
	v_and_b32_e32 v220, 0xffff0000, v54
	v_and_b32_e32 v221, 0xffff0000, v58
	v_add_f32_e32 v220, v220, v221
	v_add_f32_e32 v190, v190, v220
	v_lshlrev_b32_e32 v218, 16, v55
	v_lshlrev_b32_e32 v219, 16, v59
	v_add_f32_e32 v218, v218, v219
	v_add_f32_e32 v190, v190, v218
	v_and_b32_e32 v220, 0xffff0000, v55
	v_and_b32_e32 v221, 0xffff0000, v59
	v_add_f32_e32 v220, v220, v221
	v_add_f32_e32 v190, v190, v220
	v_mov_b32_e32 v191, 0
	v_lshlrev_b32_e32 v218, 16, v60
	v_lshlrev_b32_e32 v219, 16, v64
	v_add_f32_e32 v218, v218, v219
	v_add_f32_e32 v191, v191, v218
	v_and_b32_e32 v220, 0xffff0000, v60
	v_and_b32_e32 v221, 0xffff0000, v64
	v_add_f32_e32 v220, v220, v221
	v_add_f32_e32 v191, v191, v220
	v_lshlrev_b32_e32 v218, 16, v61
	v_lshlrev_b32_e32 v219, 16, v65
	v_add_f32_e32 v218, v218, v219
	v_add_f32_e32 v191, v191, v218
	v_and_b32_e32 v220, 0xffff0000, v61
	v_and_b32_e32 v221, 0xffff0000, v65
	v_add_f32_e32 v220, v220, v221
	v_add_f32_e32 v191, v191, v220
	v_lshlrev_b32_e32 v218, 16, v62
	v_lshlrev_b32_e32 v219, 16, v66
	v_add_f32_e32 v218, v218, v219
	v_add_f32_e32 v191, v191, v218
	v_and_b32_e32 v220, 0xffff0000, v62
	v_and_b32_e32 v221, 0xffff0000, v66
	v_add_f32_e32 v220, v220, v221
	v_add_f32_e32 v191, v191, v220
	v_lshlrev_b32_e32 v218, 16, v63
	v_lshlrev_b32_e32 v219, 16, v67
	v_add_f32_e32 v218, v218, v219
	v_add_f32_e32 v191, v191, v218
	v_and_b32_e32 v220, 0xffff0000, v63
	v_and_b32_e32 v221, 0xffff0000, v67
	v_add_f32_e32 v220, v220, v221
	v_add_f32_e32 v191, v191, v220
	v_mov_b32_e32 v192, 0
	v_lshlrev_b32_e32 v218, 16, v68
	v_lshlrev_b32_e32 v219, 16, v72
	v_add_f32_e32 v218, v218, v219
	v_add_f32_e32 v192, v192, v218
	v_and_b32_e32 v220, 0xffff0000, v68
	v_and_b32_e32 v221, 0xffff0000, v72
	v_add_f32_e32 v220, v220, v221
	v_add_f32_e32 v192, v192, v220
	v_lshlrev_b32_e32 v218, 16, v69
	v_lshlrev_b32_e32 v219, 16, v73
	v_add_f32_e32 v218, v218, v219
	v_add_f32_e32 v192, v192, v218
	v_and_b32_e32 v220, 0xffff0000, v69
	v_and_b32_e32 v221, 0xffff0000, v73
	v_add_f32_e32 v220, v220, v221
	v_add_f32_e32 v192, v192, v220
	v_lshlrev_b32_e32 v218, 16, v70
	v_lshlrev_b32_e32 v219, 16, v74
	v_add_f32_e32 v218, v218, v219
	v_add_f32_e32 v192, v192, v218
	v_and_b32_e32 v220, 0xffff0000, v70
	v_and_b32_e32 v221, 0xffff0000, v74
	v_add_f32_e32 v220, v220, v221
	v_add_f32_e32 v192, v192, v220
	v_lshlrev_b32_e32 v218, 16, v71
	v_lshlrev_b32_e32 v219, 16, v75
	v_add_f32_e32 v218, v218, v219
	v_add_f32_e32 v192, v192, v218
	v_and_b32_e32 v220, 0xffff0000, v71
	v_and_b32_e32 v221, 0xffff0000, v75
	v_add_f32_e32 v220, v220, v221
	v_add_f32_e32 v192, v192, v220
	v_mov_b32_e32 v193, 0
	v_lshlrev_b32_e32 v218, 16, v76
	v_lshlrev_b32_e32 v219, 16, v80
	v_add_f32_e32 v218, v218, v219
	v_add_f32_e32 v193, v193, v218
	v_and_b32_e32 v220, 0xffff0000, v76
	v_and_b32_e32 v221, 0xffff0000, v80
	v_add_f32_e32 v220, v220, v221
	v_add_f32_e32 v193, v193, v220
	v_lshlrev_b32_e32 v218, 16, v77
	v_lshlrev_b32_e32 v219, 16, v81
	v_add_f32_e32 v218, v218, v219
	v_add_f32_e32 v193, v193, v218
	v_and_b32_e32 v220, 0xffff0000, v77
	v_and_b32_e32 v221, 0xffff0000, v81
	v_add_f32_e32 v220, v220, v221
	v_add_f32_e32 v193, v193, v220
	v_lshlrev_b32_e32 v218, 16, v78
	v_lshlrev_b32_e32 v219, 16, v82
	v_add_f32_e32 v218, v218, v219
	v_add_f32_e32 v193, v193, v218
	v_and_b32_e32 v220, 0xffff0000, v78
	v_and_b32_e32 v221, 0xffff0000, v82
	v_add_f32_e32 v220, v220, v221
	v_add_f32_e32 v193, v193, v220
	v_lshlrev_b32_e32 v218, 16, v79
	v_lshlrev_b32_e32 v219, 16, v83
	v_add_f32_e32 v218, v218, v219
	v_add_f32_e32 v193, v193, v218
	v_and_b32_e32 v220, 0xffff0000, v79
	v_and_b32_e32 v221, 0xffff0000, v83
	v_add_f32_e32 v220, v220, v221
	v_add_f32_e32 v193, v193, v220
	v_xor_b32_e32 v229, 4, v228
	ds_bpermute_b32 v194, v229, v186
	ds_bpermute_b32 v195, v229, v187
	ds_bpermute_b32 v196, v229, v188
	ds_bpermute_b32 v197, v229, v189
	ds_bpermute_b32 v198, v229, v190
	ds_bpermute_b32 v199, v229, v191
	ds_bpermute_b32 v200, v229, v192
	ds_bpermute_b32 v201, v229, v193
	s_waitcnt lgkmcnt(0)
	v_add_f32_e32 v186, v186, v194
	v_add_f32_e32 v187, v187, v195
	v_add_f32_e32 v188, v188, v196
	v_add_f32_e32 v189, v189, v197
	v_add_f32_e32 v190, v190, v198
	v_add_f32_e32 v191, v191, v199
	v_add_f32_e32 v192, v192, v200
	v_add_f32_e32 v193, v193, v201
	v_xor_b32_e32 v229, 8, v228
	ds_bpermute_b32 v194, v229, v186
	ds_bpermute_b32 v195, v229, v187
	ds_bpermute_b32 v196, v229, v188
	ds_bpermute_b32 v197, v229, v189
	ds_bpermute_b32 v198, v229, v190
	ds_bpermute_b32 v199, v229, v191
	ds_bpermute_b32 v200, v229, v192
	ds_bpermute_b32 v201, v229, v193
	s_waitcnt lgkmcnt(0)
	v_add_f32_e32 v186, v186, v194
	v_add_f32_e32 v187, v187, v195
	v_add_f32_e32 v188, v188, v196
	v_add_f32_e32 v189, v189, v197
	v_add_f32_e32 v190, v190, v198
	v_add_f32_e32 v191, v191, v199
	v_add_f32_e32 v192, v192, v200
	v_add_f32_e32 v193, v193, v201
	v_xor_b32_e32 v229, 16, v228
	ds_bpermute_b32 v194, v229, v186
	ds_bpermute_b32 v195, v229, v187
	ds_bpermute_b32 v196, v229, v188
	ds_bpermute_b32 v197, v229, v189
	ds_bpermute_b32 v198, v229, v190
	ds_bpermute_b32 v199, v229, v191
	ds_bpermute_b32 v200, v229, v192
	ds_bpermute_b32 v201, v229, v193
	s_waitcnt lgkmcnt(0)
	v_add_f32_e32 v186, v186, v194
	v_add_f32_e32 v187, v187, v195
	v_add_f32_e32 v188, v188, v196
	v_add_f32_e32 v189, v189, v197
	v_add_f32_e32 v190, v190, v198
	v_add_f32_e32 v191, v191, v199
	v_add_f32_e32 v192, v192, v200
	v_add_f32_e32 v193, v193, v201
	v_xor_b32_e32 v229, 32, v228
	ds_bpermute_b32 v194, v229, v186
	ds_bpermute_b32 v195, v229, v187
	ds_bpermute_b32 v196, v229, v188
	ds_bpermute_b32 v197, v229, v189
	ds_bpermute_b32 v198, v229, v190
	ds_bpermute_b32 v199, v229, v191
	ds_bpermute_b32 v200, v229, v192
	ds_bpermute_b32 v201, v229, v193
	s_waitcnt lgkmcnt(0)
	v_add_f32_e32 v186, v186, v194
	v_add_f32_e32 v187, v187, v195
	v_add_f32_e32 v188, v188, v196
	v_add_f32_e32 v189, v189, v197
	v_add_f32_e32 v190, v190, v198
	v_add_f32_e32 v191, v191, v199
	v_add_f32_e32 v192, v192, v200
	v_add_f32_e32 v193, v193, v201
	v_xor_b32_e32 v229, 64, v228
	ds_bpermute_b32 v194, v229, v186
	ds_bpermute_b32 v195, v229, v187
	ds_bpermute_b32 v196, v229, v188
	ds_bpermute_b32 v197, v229, v189
	ds_bpermute_b32 v198, v229, v190
	ds_bpermute_b32 v199, v229, v191
	ds_bpermute_b32 v200, v229, v192
	ds_bpermute_b32 v201, v229, v193
	s_waitcnt lgkmcnt(0)
	v_add_f32_e32 v186, v186, v194
	v_add_f32_e32 v187, v187, v195
	v_add_f32_e32 v188, v188, v196
	v_add_f32_e32 v189, v189, v197
	v_add_f32_e32 v190, v190, v198
	v_add_f32_e32 v191, v191, v199
	v_add_f32_e32 v192, v192, v200
	v_add_f32_e32 v193, v193, v201
	v_xor_b32_e32 v229, 128, v228
	ds_bpermute_b32 v194, v229, v186
	ds_bpermute_b32 v195, v229, v187
	ds_bpermute_b32 v196, v229, v188
	ds_bpermute_b32 v197, v229, v189
	ds_bpermute_b32 v198, v229, v190
	ds_bpermute_b32 v199, v229, v191
	ds_bpermute_b32 v200, v229, v192
	ds_bpermute_b32 v201, v229, v193
	s_waitcnt lgkmcnt(0)
	v_add_f32_e32 v186, v186, v194
	v_add_f32_e32 v187, v187, v195
	v_add_f32_e32 v188, v188, v196
	v_add_f32_e32 v189, v189, v197
	v_add_f32_e32 v190, v190, v198
	v_add_f32_e32 v191, v191, v199
	v_add_f32_e32 v192, v192, v200
	v_add_f32_e32 v193, v193, v201
	v_mov_b32_e32 v225, 0x3a800000
	v_mul_f32_e32 v202, v186, v225
	v_mul_f32_e32 v203, v187, v225
	v_mul_f32_e32 v204, v188, v225
	v_mul_f32_e32 v205, v189, v225
	v_mul_f32_e32 v206, v190, v225
	v_mul_f32_e32 v207, v191, v225
	v_mul_f32_e32 v208, v192, v225
	v_mul_f32_e32 v209, v193, v225
	v_mov_b32_e32 v186, 0
	v_lshlrev_b32_e32 v218, 16, v16
	v_lshlrev_b32_e32 v219, 16, v20
	v_sub_f32_e32 v218, v218, v202
	v_sub_f32_e32 v219, v219, v202
	v_mul_f32_e32 v219, v219, v219
	v_fma_f32 v219, v218, v218, v219
	v_add_f32_e32 v186, v186, v219
	v_and_b32_e32 v218, 0xffff0000, v16
	v_and_b32_e32 v219, 0xffff0000, v20
	v_sub_f32_e32 v218, v218, v202
	v_sub_f32_e32 v219, v219, v202
	v_mul_f32_e32 v219, v219, v219
	v_fma_f32 v219, v218, v218, v219
	v_add_f32_e32 v186, v186, v219
	v_lshlrev_b32_e32 v218, 16, v17
	v_lshlrev_b32_e32 v219, 16, v21
	v_sub_f32_e32 v218, v218, v202
	v_sub_f32_e32 v219, v219, v202
	v_mul_f32_e32 v219, v219, v219
	v_fma_f32 v219, v218, v218, v219
	v_add_f32_e32 v186, v186, v219
	v_and_b32_e32 v218, 0xffff0000, v17
	v_and_b32_e32 v219, 0xffff0000, v21
	v_sub_f32_e32 v218, v218, v202
	v_sub_f32_e32 v219, v219, v202
	v_mul_f32_e32 v219, v219, v219
	v_fma_f32 v219, v218, v218, v219
	v_add_f32_e32 v186, v186, v219
	v_lshlrev_b32_e32 v218, 16, v18
	v_lshlrev_b32_e32 v219, 16, v22
	v_sub_f32_e32 v218, v218, v202
	v_sub_f32_e32 v219, v219, v202
	v_mul_f32_e32 v219, v219, v219
	v_fma_f32 v219, v218, v218, v219
	v_add_f32_e32 v186, v186, v219
	v_and_b32_e32 v218, 0xffff0000, v18
	v_and_b32_e32 v219, 0xffff0000, v22
	v_sub_f32_e32 v218, v218, v202
	v_sub_f32_e32 v219, v219, v202
	v_mul_f32_e32 v219, v219, v219
	v_fma_f32 v219, v218, v218, v219
	v_add_f32_e32 v186, v186, v219
	v_lshlrev_b32_e32 v218, 16, v19
	v_lshlrev_b32_e32 v219, 16, v23
	v_sub_f32_e32 v218, v218, v202
	v_sub_f32_e32 v219, v219, v202
	v_mul_f32_e32 v219, v219, v219
	v_fma_f32 v219, v218, v218, v219
	v_add_f32_e32 v186, v186, v219
	v_and_b32_e32 v218, 0xffff0000, v19
	v_and_b32_e32 v219, 0xffff0000, v23
	v_sub_f32_e32 v218, v218, v202
	v_sub_f32_e32 v219, v219, v202
	v_mul_f32_e32 v219, v219, v219
	v_fma_f32 v219, v218, v218, v219
	v_add_f32_e32 v186, v186, v219
	v_mov_b32_e32 v187, 0
	v_lshlrev_b32_e32 v218, 16, v24
	v_lshlrev_b32_e32 v219, 16, v28
	v_sub_f32_e32 v218, v218, v203
	v_sub_f32_e32 v219, v219, v203
	v_mul_f32_e32 v219, v219, v219
	v_fma_f32 v219, v218, v218, v219
	v_add_f32_e32 v187, v187, v219
	v_and_b32_e32 v218, 0xffff0000, v24
	v_and_b32_e32 v219, 0xffff0000, v28
	v_sub_f32_e32 v218, v218, v203
	v_sub_f32_e32 v219, v219, v203
	v_mul_f32_e32 v219, v219, v219
	v_fma_f32 v219, v218, v218, v219
	v_add_f32_e32 v187, v187, v219
	v_lshlrev_b32_e32 v218, 16, v25
	v_lshlrev_b32_e32 v219, 16, v29
	v_sub_f32_e32 v218, v218, v203
	v_sub_f32_e32 v219, v219, v203
	v_mul_f32_e32 v219, v219, v219
	v_fma_f32 v219, v218, v218, v219
	v_add_f32_e32 v187, v187, v219
	v_and_b32_e32 v218, 0xffff0000, v25
	v_and_b32_e32 v219, 0xffff0000, v29
	v_sub_f32_e32 v218, v218, v203
	v_sub_f32_e32 v219, v219, v203
	v_mul_f32_e32 v219, v219, v219
	v_fma_f32 v219, v218, v218, v219
	v_add_f32_e32 v187, v187, v219
	v_lshlrev_b32_e32 v218, 16, v26
	v_lshlrev_b32_e32 v219, 16, v30
	v_sub_f32_e32 v218, v218, v203
	v_sub_f32_e32 v219, v219, v203
	v_mul_f32_e32 v219, v219, v219
	v_fma_f32 v219, v218, v218, v219
	v_add_f32_e32 v187, v187, v219
	v_and_b32_e32 v218, 0xffff0000, v26
	v_and_b32_e32 v219, 0xffff0000, v30
	v_sub_f32_e32 v218, v218, v203
	v_sub_f32_e32 v219, v219, v203
	v_mul_f32_e32 v219, v219, v219
	v_fma_f32 v219, v218, v218, v219
	v_add_f32_e32 v187, v187, v219
	v_lshlrev_b32_e32 v218, 16, v27
	v_lshlrev_b32_e32 v219, 16, v31
	v_sub_f32_e32 v218, v218, v203
	v_sub_f32_e32 v219, v219, v203
	v_mul_f32_e32 v219, v219, v219
	v_fma_f32 v219, v218, v218, v219
	v_add_f32_e32 v187, v187, v219
	v_and_b32_e32 v218, 0xffff0000, v27
	v_and_b32_e32 v219, 0xffff0000, v31
	v_sub_f32_e32 v218, v218, v203
	v_sub_f32_e32 v219, v219, v203
	v_mul_f32_e32 v219, v219, v219
	v_fma_f32 v219, v218, v218, v219
	v_add_f32_e32 v187, v187, v219
	v_mov_b32_e32 v188, 0
	v_lshlrev_b32_e32 v218, 16, v36
	v_lshlrev_b32_e32 v219, 16, v40
	v_sub_f32_e32 v218, v218, v204
	v_sub_f32_e32 v219, v219, v204
	v_mul_f32_e32 v219, v219, v219
	v_fma_f32 v219, v218, v218, v219
	v_add_f32_e32 v188, v188, v219
	v_and_b32_e32 v218, 0xffff0000, v36
	v_and_b32_e32 v219, 0xffff0000, v40
	v_sub_f32_e32 v218, v218, v204
	v_sub_f32_e32 v219, v219, v204
	v_mul_f32_e32 v219, v219, v219
	v_fma_f32 v219, v218, v218, v219
	v_add_f32_e32 v188, v188, v219
	v_lshlrev_b32_e32 v218, 16, v37
	v_lshlrev_b32_e32 v219, 16, v41
	v_sub_f32_e32 v218, v218, v204
	v_sub_f32_e32 v219, v219, v204
	v_mul_f32_e32 v219, v219, v219
	v_fma_f32 v219, v218, v218, v219
	v_add_f32_e32 v188, v188, v219
	v_and_b32_e32 v218, 0xffff0000, v37
	v_and_b32_e32 v219, 0xffff0000, v41
	v_sub_f32_e32 v218, v218, v204
	v_sub_f32_e32 v219, v219, v204
	v_mul_f32_e32 v219, v219, v219
	v_fma_f32 v219, v218, v218, v219
	v_add_f32_e32 v188, v188, v219
	v_lshlrev_b32_e32 v218, 16, v38
	v_lshlrev_b32_e32 v219, 16, v42
	v_sub_f32_e32 v218, v218, v204
	v_sub_f32_e32 v219, v219, v204
	v_mul_f32_e32 v219, v219, v219
	v_fma_f32 v219, v218, v218, v219
	v_add_f32_e32 v188, v188, v219
	v_and_b32_e32 v218, 0xffff0000, v38
	v_and_b32_e32 v219, 0xffff0000, v42
	v_sub_f32_e32 v218, v218, v204
	v_sub_f32_e32 v219, v219, v204
	v_mul_f32_e32 v219, v219, v219
	v_fma_f32 v219, v218, v218, v219
	v_add_f32_e32 v188, v188, v219
	v_lshlrev_b32_e32 v218, 16, v39
	v_lshlrev_b32_e32 v219, 16, v43
	v_sub_f32_e32 v218, v218, v204
	v_sub_f32_e32 v219, v219, v204
	v_mul_f32_e32 v219, v219, v219
	v_fma_f32 v219, v218, v218, v219
	v_add_f32_e32 v188, v188, v219
	v_and_b32_e32 v218, 0xffff0000, v39
	v_and_b32_e32 v219, 0xffff0000, v43
	v_sub_f32_e32 v218, v218, v204
	v_sub_f32_e32 v219, v219, v204
	v_mul_f32_e32 v219, v219, v219
	v_fma_f32 v219, v218, v218, v219
	v_add_f32_e32 v188, v188, v219
	v_mov_b32_e32 v189, 0
	v_lshlrev_b32_e32 v218, 16, v44
	v_lshlrev_b32_e32 v219, 16, v48
	v_sub_f32_e32 v218, v218, v205
	v_sub_f32_e32 v219, v219, v205
	v_mul_f32_e32 v219, v219, v219
	v_fma_f32 v219, v218, v218, v219
	v_add_f32_e32 v189, v189, v219
	v_and_b32_e32 v218, 0xffff0000, v44
	v_and_b32_e32 v219, 0xffff0000, v48
	v_sub_f32_e32 v218, v218, v205
	v_sub_f32_e32 v219, v219, v205
	v_mul_f32_e32 v219, v219, v219
	v_fma_f32 v219, v218, v218, v219
	v_add_f32_e32 v189, v189, v219
	v_lshlrev_b32_e32 v218, 16, v45
	v_lshlrev_b32_e32 v219, 16, v49
	v_sub_f32_e32 v218, v218, v205
	v_sub_f32_e32 v219, v219, v205
	v_mul_f32_e32 v219, v219, v219
	v_fma_f32 v219, v218, v218, v219
	v_add_f32_e32 v189, v189, v219
	v_and_b32_e32 v218, 0xffff0000, v45
	v_and_b32_e32 v219, 0xffff0000, v49
	v_sub_f32_e32 v218, v218, v205
	v_sub_f32_e32 v219, v219, v205
	v_mul_f32_e32 v219, v219, v219
	v_fma_f32 v219, v218, v218, v219
	v_add_f32_e32 v189, v189, v219
	v_lshlrev_b32_e32 v218, 16, v46
	v_lshlrev_b32_e32 v219, 16, v50
	v_sub_f32_e32 v218, v218, v205
	v_sub_f32_e32 v219, v219, v205
	v_mul_f32_e32 v219, v219, v219
	v_fma_f32 v219, v218, v218, v219
	v_add_f32_e32 v189, v189, v219
	v_and_b32_e32 v218, 0xffff0000, v46
	v_and_b32_e32 v219, 0xffff0000, v50
	v_sub_f32_e32 v218, v218, v205
	v_sub_f32_e32 v219, v219, v205
	v_mul_f32_e32 v219, v219, v219
	v_fma_f32 v219, v218, v218, v219
	v_add_f32_e32 v189, v189, v219
	v_lshlrev_b32_e32 v218, 16, v47
	v_lshlrev_b32_e32 v219, 16, v51
	v_sub_f32_e32 v218, v218, v205
	v_sub_f32_e32 v219, v219, v205
	v_mul_f32_e32 v219, v219, v219
	v_fma_f32 v219, v218, v218, v219
	v_add_f32_e32 v189, v189, v219
	v_and_b32_e32 v218, 0xffff0000, v47
	v_and_b32_e32 v219, 0xffff0000, v51
	v_sub_f32_e32 v218, v218, v205
	v_sub_f32_e32 v219, v219, v205
	v_mul_f32_e32 v219, v219, v219
	v_fma_f32 v219, v218, v218, v219
	v_add_f32_e32 v189, v189, v219
	v_mov_b32_e32 v190, 0
	v_lshlrev_b32_e32 v218, 16, v52
	v_lshlrev_b32_e32 v219, 16, v56
	v_sub_f32_e32 v218, v218, v206
	v_sub_f32_e32 v219, v219, v206
	v_mul_f32_e32 v219, v219, v219
	v_fma_f32 v219, v218, v218, v219
	v_add_f32_e32 v190, v190, v219
	v_and_b32_e32 v218, 0xffff0000, v52
	v_and_b32_e32 v219, 0xffff0000, v56
	v_sub_f32_e32 v218, v218, v206
	v_sub_f32_e32 v219, v219, v206
	v_mul_f32_e32 v219, v219, v219
	v_fma_f32 v219, v218, v218, v219
	v_add_f32_e32 v190, v190, v219
	v_lshlrev_b32_e32 v218, 16, v53
	v_lshlrev_b32_e32 v219, 16, v57
	v_sub_f32_e32 v218, v218, v206
	v_sub_f32_e32 v219, v219, v206
	v_mul_f32_e32 v219, v219, v219
	v_fma_f32 v219, v218, v218, v219
	v_add_f32_e32 v190, v190, v219
	v_and_b32_e32 v218, 0xffff0000, v53
	v_and_b32_e32 v219, 0xffff0000, v57
	v_sub_f32_e32 v218, v218, v206
	v_sub_f32_e32 v219, v219, v206
	v_mul_f32_e32 v219, v219, v219
	v_fma_f32 v219, v218, v218, v219
	v_add_f32_e32 v190, v190, v219
	v_lshlrev_b32_e32 v218, 16, v54
	v_lshlrev_b32_e32 v219, 16, v58
	v_sub_f32_e32 v218, v218, v206
	v_sub_f32_e32 v219, v219, v206
	v_mul_f32_e32 v219, v219, v219
	v_fma_f32 v219, v218, v218, v219
	v_add_f32_e32 v190, v190, v219
	v_and_b32_e32 v218, 0xffff0000, v54
	v_and_b32_e32 v219, 0xffff0000, v58
	v_sub_f32_e32 v218, v218, v206
	v_sub_f32_e32 v219, v219, v206
	v_mul_f32_e32 v219, v219, v219
	v_fma_f32 v219, v218, v218, v219
	v_add_f32_e32 v190, v190, v219
	v_lshlrev_b32_e32 v218, 16, v55
	v_lshlrev_b32_e32 v219, 16, v59
	v_sub_f32_e32 v218, v218, v206
	v_sub_f32_e32 v219, v219, v206
	v_mul_f32_e32 v219, v219, v219
	v_fma_f32 v219, v218, v218, v219
	v_add_f32_e32 v190, v190, v219
	v_and_b32_e32 v218, 0xffff0000, v55
	v_and_b32_e32 v219, 0xffff0000, v59
	v_sub_f32_e32 v218, v218, v206
	v_sub_f32_e32 v219, v219, v206
	v_mul_f32_e32 v219, v219, v219
	v_fma_f32 v219, v218, v218, v219
	v_add_f32_e32 v190, v190, v219
	v_mov_b32_e32 v191, 0
	v_lshlrev_b32_e32 v218, 16, v60
	v_lshlrev_b32_e32 v219, 16, v64
	v_sub_f32_e32 v218, v218, v207
	v_sub_f32_e32 v219, v219, v207
	v_mul_f32_e32 v219, v219, v219
	v_fma_f32 v219, v218, v218, v219
	v_add_f32_e32 v191, v191, v219
	v_and_b32_e32 v218, 0xffff0000, v60
	v_and_b32_e32 v219, 0xffff0000, v64
	v_sub_f32_e32 v218, v218, v207
	v_sub_f32_e32 v219, v219, v207
	v_mul_f32_e32 v219, v219, v219
	v_fma_f32 v219, v218, v218, v219
	v_add_f32_e32 v191, v191, v219
	v_lshlrev_b32_e32 v218, 16, v61
	v_lshlrev_b32_e32 v219, 16, v65
	v_sub_f32_e32 v218, v218, v207
	v_sub_f32_e32 v219, v219, v207
	v_mul_f32_e32 v219, v219, v219
	v_fma_f32 v219, v218, v218, v219
	v_add_f32_e32 v191, v191, v219
	v_and_b32_e32 v218, 0xffff0000, v61
	v_and_b32_e32 v219, 0xffff0000, v65
	v_sub_f32_e32 v218, v218, v207
	v_sub_f32_e32 v219, v219, v207
	v_mul_f32_e32 v219, v219, v219
	v_fma_f32 v219, v218, v218, v219
	v_add_f32_e32 v191, v191, v219
	v_lshlrev_b32_e32 v218, 16, v62
	v_lshlrev_b32_e32 v219, 16, v66
	v_sub_f32_e32 v218, v218, v207
	v_sub_f32_e32 v219, v219, v207
	v_mul_f32_e32 v219, v219, v219
	v_fma_f32 v219, v218, v218, v219
	v_add_f32_e32 v191, v191, v219
	v_and_b32_e32 v218, 0xffff0000, v62
	v_and_b32_e32 v219, 0xffff0000, v66
	v_sub_f32_e32 v218, v218, v207
	v_sub_f32_e32 v219, v219, v207
	v_mul_f32_e32 v219, v219, v219
	v_fma_f32 v219, v218, v218, v219
	v_add_f32_e32 v191, v191, v219
	v_lshlrev_b32_e32 v218, 16, v63
	v_lshlrev_b32_e32 v219, 16, v67
	v_sub_f32_e32 v218, v218, v207
	v_sub_f32_e32 v219, v219, v207
	v_mul_f32_e32 v219, v219, v219
	v_fma_f32 v219, v218, v218, v219
	v_add_f32_e32 v191, v191, v219
	v_and_b32_e32 v218, 0xffff0000, v63
	v_and_b32_e32 v219, 0xffff0000, v67
	v_sub_f32_e32 v218, v218, v207
	v_sub_f32_e32 v219, v219, v207
	v_mul_f32_e32 v219, v219, v219
	v_fma_f32 v219, v218, v218, v219
	v_add_f32_e32 v191, v191, v219
	v_mov_b32_e32 v192, 0
	v_lshlrev_b32_e32 v218, 16, v68
	v_lshlrev_b32_e32 v219, 16, v72
	v_sub_f32_e32 v218, v218, v208
	v_sub_f32_e32 v219, v219, v208
	v_mul_f32_e32 v219, v219, v219
	v_fma_f32 v219, v218, v218, v219
	v_add_f32_e32 v192, v192, v219
	v_and_b32_e32 v218, 0xffff0000, v68
	v_and_b32_e32 v219, 0xffff0000, v72
	v_sub_f32_e32 v218, v218, v208
	v_sub_f32_e32 v219, v219, v208
	v_mul_f32_e32 v219, v219, v219
	v_fma_f32 v219, v218, v218, v219
	v_add_f32_e32 v192, v192, v219
	v_lshlrev_b32_e32 v218, 16, v69
	v_lshlrev_b32_e32 v219, 16, v73
	v_sub_f32_e32 v218, v218, v208
	v_sub_f32_e32 v219, v219, v208
	v_mul_f32_e32 v219, v219, v219
	v_fma_f32 v219, v218, v218, v219
	v_add_f32_e32 v192, v192, v219
	v_and_b32_e32 v218, 0xffff0000, v69
	v_and_b32_e32 v219, 0xffff0000, v73
	v_sub_f32_e32 v218, v218, v208
	v_sub_f32_e32 v219, v219, v208
	v_mul_f32_e32 v219, v219, v219
	v_fma_f32 v219, v218, v218, v219
	v_add_f32_e32 v192, v192, v219
	v_lshlrev_b32_e32 v218, 16, v70
	v_lshlrev_b32_e32 v219, 16, v74
	v_sub_f32_e32 v218, v218, v208
	v_sub_f32_e32 v219, v219, v208
	v_mul_f32_e32 v219, v219, v219
	v_fma_f32 v219, v218, v218, v219
	v_add_f32_e32 v192, v192, v219
	v_and_b32_e32 v218, 0xffff0000, v70
	v_and_b32_e32 v219, 0xffff0000, v74
	v_sub_f32_e32 v218, v218, v208
	v_sub_f32_e32 v219, v219, v208
	v_mul_f32_e32 v219, v219, v219
	v_fma_f32 v219, v218, v218, v219
	v_add_f32_e32 v192, v192, v219
	v_lshlrev_b32_e32 v218, 16, v71
	v_lshlrev_b32_e32 v219, 16, v75
	v_sub_f32_e32 v218, v218, v208
	v_sub_f32_e32 v219, v219, v208
	v_mul_f32_e32 v219, v219, v219
	v_fma_f32 v219, v218, v218, v219
	v_add_f32_e32 v192, v192, v219
	v_and_b32_e32 v218, 0xffff0000, v71
	v_and_b32_e32 v219, 0xffff0000, v75
	v_sub_f32_e32 v218, v218, v208
	v_sub_f32_e32 v219, v219, v208
	v_mul_f32_e32 v219, v219, v219
	v_fma_f32 v219, v218, v218, v219
	v_add_f32_e32 v192, v192, v219
	v_mov_b32_e32 v193, 0
	v_lshlrev_b32_e32 v218, 16, v76
	v_lshlrev_b32_e32 v219, 16, v80
	v_sub_f32_e32 v218, v218, v209
	v_sub_f32_e32 v219, v219, v209
	v_mul_f32_e32 v219, v219, v219
	v_fma_f32 v219, v218, v218, v219
	v_add_f32_e32 v193, v193, v219
	v_and_b32_e32 v218, 0xffff0000, v76
	v_and_b32_e32 v219, 0xffff0000, v80
	v_sub_f32_e32 v218, v218, v209
	v_sub_f32_e32 v219, v219, v209
	v_mul_f32_e32 v219, v219, v219
	v_fma_f32 v219, v218, v218, v219
	v_add_f32_e32 v193, v193, v219
	v_lshlrev_b32_e32 v218, 16, v77
	v_lshlrev_b32_e32 v219, 16, v81
	v_sub_f32_e32 v218, v218, v209
	v_sub_f32_e32 v219, v219, v209
	v_mul_f32_e32 v219, v219, v219
	v_fma_f32 v219, v218, v218, v219
	v_add_f32_e32 v193, v193, v219
	v_and_b32_e32 v218, 0xffff0000, v77
	v_and_b32_e32 v219, 0xffff0000, v81
	v_sub_f32_e32 v218, v218, v209
	v_sub_f32_e32 v219, v219, v209
	v_mul_f32_e32 v219, v219, v219
	v_fma_f32 v219, v218, v218, v219
	v_add_f32_e32 v193, v193, v219
	v_lshlrev_b32_e32 v218, 16, v78
	v_lshlrev_b32_e32 v219, 16, v82
	v_sub_f32_e32 v218, v218, v209
	v_sub_f32_e32 v219, v219, v209
	v_mul_f32_e32 v219, v219, v219
	v_fma_f32 v219, v218, v218, v219
	v_add_f32_e32 v193, v193, v219
	v_and_b32_e32 v218, 0xffff0000, v78
	v_and_b32_e32 v219, 0xffff0000, v82
	v_sub_f32_e32 v218, v218, v209
	v_sub_f32_e32 v219, v219, v209
	v_mul_f32_e32 v219, v219, v219
	v_fma_f32 v219, v218, v218, v219
	v_add_f32_e32 v193, v193, v219
	v_lshlrev_b32_e32 v218, 16, v79
	v_lshlrev_b32_e32 v219, 16, v83
	v_sub_f32_e32 v218, v218, v209
	v_sub_f32_e32 v219, v219, v209
	v_mul_f32_e32 v219, v219, v219
	v_fma_f32 v219, v218, v218, v219
	v_add_f32_e32 v193, v193, v219
	v_and_b32_e32 v218, 0xffff0000, v79
	v_and_b32_e32 v219, 0xffff0000, v83
	v_sub_f32_e32 v218, v218, v209
	v_sub_f32_e32 v219, v219, v209
	v_mul_f32_e32 v219, v219, v219
	v_fma_f32 v219, v218, v218, v219
	v_add_f32_e32 v193, v193, v219
	v_xor_b32_e32 v229, 4, v228
	ds_bpermute_b32 v194, v229, v186
	ds_bpermute_b32 v195, v229, v187
	ds_bpermute_b32 v196, v229, v188
	ds_bpermute_b32 v197, v229, v189
	ds_bpermute_b32 v198, v229, v190
	ds_bpermute_b32 v199, v229, v191
	ds_bpermute_b32 v200, v229, v192
	ds_bpermute_b32 v201, v229, v193
	s_waitcnt lgkmcnt(0)
	v_add_f32_e32 v186, v186, v194
	v_add_f32_e32 v187, v187, v195
	v_add_f32_e32 v188, v188, v196
	v_add_f32_e32 v189, v189, v197
	v_add_f32_e32 v190, v190, v198
	v_add_f32_e32 v191, v191, v199
	v_add_f32_e32 v192, v192, v200
	v_add_f32_e32 v193, v193, v201
	v_xor_b32_e32 v229, 8, v228
	ds_bpermute_b32 v194, v229, v186
	ds_bpermute_b32 v195, v229, v187
	ds_bpermute_b32 v196, v229, v188
	ds_bpermute_b32 v197, v229, v189
	ds_bpermute_b32 v198, v229, v190
	ds_bpermute_b32 v199, v229, v191
	ds_bpermute_b32 v200, v229, v192
	ds_bpermute_b32 v201, v229, v193
	s_waitcnt lgkmcnt(0)
	v_add_f32_e32 v186, v186, v194
	v_add_f32_e32 v187, v187, v195
	v_add_f32_e32 v188, v188, v196
	v_add_f32_e32 v189, v189, v197
	v_add_f32_e32 v190, v190, v198
	v_add_f32_e32 v191, v191, v199
	v_add_f32_e32 v192, v192, v200
	v_add_f32_e32 v193, v193, v201
	v_xor_b32_e32 v229, 16, v228
	ds_bpermute_b32 v194, v229, v186
	ds_bpermute_b32 v195, v229, v187
	ds_bpermute_b32 v196, v229, v188
	ds_bpermute_b32 v197, v229, v189
	ds_bpermute_b32 v198, v229, v190
	ds_bpermute_b32 v199, v229, v191
	ds_bpermute_b32 v200, v229, v192
	ds_bpermute_b32 v201, v229, v193
	s_waitcnt lgkmcnt(0)
	v_add_f32_e32 v186, v186, v194
	v_add_f32_e32 v187, v187, v195
	v_add_f32_e32 v188, v188, v196
	v_add_f32_e32 v189, v189, v197
	v_add_f32_e32 v190, v190, v198
	v_add_f32_e32 v191, v191, v199
	v_add_f32_e32 v192, v192, v200
	v_add_f32_e32 v193, v193, v201
	v_xor_b32_e32 v229, 32, v228
	ds_bpermute_b32 v194, v229, v186
	ds_bpermute_b32 v195, v229, v187
	ds_bpermute_b32 v196, v229, v188
	ds_bpermute_b32 v197, v229, v189
	ds_bpermute_b32 v198, v229, v190
	ds_bpermute_b32 v199, v229, v191
	ds_bpermute_b32 v200, v229, v192
	ds_bpermute_b32 v201, v229, v193
	s_waitcnt lgkmcnt(0)
	v_add_f32_e32 v186, v186, v194
	v_add_f32_e32 v187, v187, v195
	v_add_f32_e32 v188, v188, v196
	v_add_f32_e32 v189, v189, v197
	v_add_f32_e32 v190, v190, v198
	v_add_f32_e32 v191, v191, v199
	v_add_f32_e32 v192, v192, v200
	v_add_f32_e32 v193, v193, v201
	v_xor_b32_e32 v229, 64, v228
	ds_bpermute_b32 v194, v229, v186
	ds_bpermute_b32 v195, v229, v187
	ds_bpermute_b32 v196, v229, v188
	ds_bpermute_b32 v197, v229, v189
	ds_bpermute_b32 v198, v229, v190
	ds_bpermute_b32 v199, v229, v191
	ds_bpermute_b32 v200, v229, v192
	ds_bpermute_b32 v201, v229, v193
	s_waitcnt lgkmcnt(0)
	v_add_f32_e32 v186, v186, v194
	v_add_f32_e32 v187, v187, v195
	v_add_f32_e32 v188, v188, v196
	v_add_f32_e32 v189, v189, v197
	v_add_f32_e32 v190, v190, v198
	v_add_f32_e32 v191, v191, v199
	v_add_f32_e32 v192, v192, v200
	v_add_f32_e32 v193, v193, v201
	v_xor_b32_e32 v229, 128, v228
	ds_bpermute_b32 v194, v229, v186
	ds_bpermute_b32 v195, v229, v187
	ds_bpermute_b32 v196, v229, v188
	ds_bpermute_b32 v197, v229, v189
	ds_bpermute_b32 v198, v229, v190
	ds_bpermute_b32 v199, v229, v191
	ds_bpermute_b32 v200, v229, v192
	ds_bpermute_b32 v201, v229, v193
	s_waitcnt lgkmcnt(0)
	v_add_f32_e32 v186, v186, v194
	v_add_f32_e32 v187, v187, v195
	v_add_f32_e32 v188, v188, v196
	v_add_f32_e32 v189, v189, v197
	v_add_f32_e32 v190, v190, v198
	v_add_f32_e32 v191, v191, v199
	v_add_f32_e32 v192, v192, v200
	v_add_f32_e32 v193, v193, v201
	v_mov_b32_e32 v224, 0x358637bd
	v_fma_f32 v210, v186, v225, v224
	v_rsq_f32_e32 v210, v210
	v_fma_f32 v211, v187, v225, v224
	v_rsq_f32_e32 v211, v211
	v_fma_f32 v212, v188, v225, v224
	v_rsq_f32_e32 v212, v212
	v_fma_f32 v213, v189, v225, v224
	v_rsq_f32_e32 v213, v213
	v_fma_f32 v214, v190, v225, v224
	v_rsq_f32_e32 v214, v214
	v_fma_f32 v215, v191, v225, v224
	v_rsq_f32_e32 v215, v215
	v_fma_f32 v216, v192, v225, v224
	v_rsq_f32_e32 v216, v216
	v_fma_f32 v217, v193, v225, v224
	v_rsq_f32_e32 v217, v217
	s_and_saveexec_b64 s[56:57], s[4:5]
	v_cndmask_b32_e64 v218, v20, v16, s[6:7]
	v_cndmask_b32_e64 v219, v21, v17, s[6:7]
	v_cndmask_b32_e64 v220, v22, v18, s[6:7]
	v_cndmask_b32_e64 v221, v23, v19, s[6:7]
	v_lshlrev_b32_e32 v222, 16, v218
	v_sub_f32_e32 v222, v222, v202
	v_mul_f32_e32 v222, v222, v210
	v_fma_f32 v222, v222, v0, v8
	v_and_b32_e32 v223, 0xffff0000, v218
	v_sub_f32_e32 v223, v223, v202
	v_mul_f32_e32 v223, v223, v210
	v_fma_f32 v223, v223, v1, v9
	v_cvt_pk_bf16_f32 v232, v222, v223
	v_lshlrev_b32_e32 v222, 16, v219
	v_sub_f32_e32 v222, v222, v202
	v_mul_f32_e32 v222, v222, v210
	v_fma_f32 v222, v222, v2, v10
	v_and_b32_e32 v223, 0xffff0000, v219
	v_sub_f32_e32 v223, v223, v202
	v_mul_f32_e32 v223, v223, v210
	v_fma_f32 v223, v223, v3, v11
	v_cvt_pk_bf16_f32 v233, v222, v223
	v_lshlrev_b32_e32 v222, 16, v220
	v_sub_f32_e32 v222, v222, v202
	v_mul_f32_e32 v222, v222, v210
	v_fma_f32 v222, v222, v4, v12
	v_and_b32_e32 v223, 0xffff0000, v220
	v_sub_f32_e32 v223, v223, v202
	v_mul_f32_e32 v223, v223, v210
	v_fma_f32 v223, v223, v5, v13
	v_cvt_pk_bf16_f32 v234, v222, v223
	v_lshlrev_b32_e32 v222, 16, v221
	v_sub_f32_e32 v222, v222, v202
	v_mul_f32_e32 v222, v222, v210
	v_fma_f32 v222, v222, v6, v14
	v_and_b32_e32 v223, 0xffff0000, v221
	v_sub_f32_e32 v223, v223, v202
	v_mul_f32_e32 v223, v223, v210
	v_fma_f32 v223, v223, v7, v15
	v_cvt_pk_bf16_f32 v235, v222, v223
	ds_write_b128 v107, v[232:235]
	v_cndmask_b32_e64 v218, v28, v24, s[6:7]
	v_cndmask_b32_e64 v219, v29, v25, s[6:7]
	v_cndmask_b32_e64 v220, v30, v26, s[6:7]
	v_cndmask_b32_e64 v221, v31, v27, s[6:7]
	v_lshlrev_b32_e32 v222, 16, v218
	v_sub_f32_e32 v222, v222, v203
	v_mul_f32_e32 v222, v222, v211
	v_fma_f32 v222, v222, v0, v8
	v_and_b32_e32 v223, 0xffff0000, v218
	v_sub_f32_e32 v223, v223, v203
	v_mul_f32_e32 v223, v223, v211
	v_fma_f32 v223, v223, v1, v9
	v_cvt_pk_bf16_f32 v236, v222, v223
	v_lshlrev_b32_e32 v222, 16, v219
	v_sub_f32_e32 v222, v222, v203
	v_mul_f32_e32 v222, v222, v211
	v_fma_f32 v222, v222, v2, v10
	v_and_b32_e32 v223, 0xffff0000, v219
	v_sub_f32_e32 v223, v223, v203
	v_mul_f32_e32 v223, v223, v211
	v_fma_f32 v223, v223, v3, v11
	v_cvt_pk_bf16_f32 v237, v222, v223
	v_lshlrev_b32_e32 v222, 16, v220
	v_sub_f32_e32 v222, v222, v203
	v_mul_f32_e32 v222, v222, v211
	v_fma_f32 v222, v222, v4, v12
	v_and_b32_e32 v223, 0xffff0000, v220
	v_sub_f32_e32 v223, v223, v203
	v_mul_f32_e32 v223, v223, v211
	v_fma_f32 v223, v223, v5, v13
	v_cvt_pk_bf16_f32 v238, v222, v223
	v_lshlrev_b32_e32 v222, 16, v221
	v_sub_f32_e32 v222, v222, v203
	v_mul_f32_e32 v222, v222, v211
	v_fma_f32 v222, v222, v6, v14
	v_and_b32_e32 v223, 0xffff0000, v221
	v_sub_f32_e32 v223, v223, v203
	v_mul_f32_e32 v223, v223, v211
	v_fma_f32 v223, v223, v7, v15
	v_cvt_pk_bf16_f32 v239, v222, v223
	ds_write_b128 v107, v[236:239] offset:528
	v_cndmask_b32_e64 v218, v40, v36, s[6:7]
	v_cndmask_b32_e64 v219, v41, v37, s[6:7]
	v_cndmask_b32_e64 v220, v42, v38, s[6:7]
	v_cndmask_b32_e64 v221, v43, v39, s[6:7]
	v_lshlrev_b32_e32 v222, 16, v218
	v_sub_f32_e32 v222, v222, v204
	v_mul_f32_e32 v222, v222, v212
	v_fma_f32 v222, v222, v0, v8
	v_and_b32_e32 v223, 0xffff0000, v218
	v_sub_f32_e32 v223, v223, v204
	v_mul_f32_e32 v223, v223, v212
	v_fma_f32 v223, v223, v1, v9
	v_cvt_pk_bf16_f32 v232, v222, v223
	v_lshlrev_b32_e32 v222, 16, v219
	v_sub_f32_e32 v222, v222, v204
	v_mul_f32_e32 v222, v222, v212
	v_fma_f32 v222, v222, v2, v10
	v_and_b32_e32 v223, 0xffff0000, v219
	v_sub_f32_e32 v223, v223, v204
	v_mul_f32_e32 v223, v223, v212
	v_fma_f32 v223, v223, v3, v11
	v_cvt_pk_bf16_f32 v233, v222, v223
	v_lshlrev_b32_e32 v222, 16, v220
	v_sub_f32_e32 v222, v222, v204
	v_mul_f32_e32 v222, v222, v212
	v_fma_f32 v222, v222, v4, v12
	v_and_b32_e32 v223, 0xffff0000, v220
	v_sub_f32_e32 v223, v223, v204
	v_mul_f32_e32 v223, v223, v212
	v_fma_f32 v223, v223, v5, v13
	v_cvt_pk_bf16_f32 v234, v222, v223
	v_lshlrev_b32_e32 v222, 16, v221
	v_sub_f32_e32 v222, v222, v204
	v_mul_f32_e32 v222, v222, v212
	v_fma_f32 v222, v222, v6, v14
	v_and_b32_e32 v223, 0xffff0000, v221
	v_sub_f32_e32 v223, v223, v204
	v_mul_f32_e32 v223, v223, v212
	v_fma_f32 v223, v223, v7, v15
	v_cvt_pk_bf16_f32 v235, v222, v223
	ds_write_b128 v107, v[232:235] offset:1056
	v_cndmask_b32_e64 v218, v48, v44, s[6:7]
	v_cndmask_b32_e64 v219, v49, v45, s[6:7]
	v_cndmask_b32_e64 v220, v50, v46, s[6:7]
	v_cndmask_b32_e64 v221, v51, v47, s[6:7]
	v_lshlrev_b32_e32 v222, 16, v218
	v_sub_f32_e32 v222, v222, v205
	v_mul_f32_e32 v222, v222, v213
	v_fma_f32 v222, v222, v0, v8
	v_and_b32_e32 v223, 0xffff0000, v218
	v_sub_f32_e32 v223, v223, v205
	v_mul_f32_e32 v223, v223, v213
	v_fma_f32 v223, v223, v1, v9
	v_cvt_pk_bf16_f32 v236, v222, v223
	v_lshlrev_b32_e32 v222, 16, v219
	v_sub_f32_e32 v222, v222, v205
	v_mul_f32_e32 v222, v222, v213
	v_fma_f32 v222, v222, v2, v10
	v_and_b32_e32 v223, 0xffff0000, v219
	v_sub_f32_e32 v223, v223, v205
	v_mul_f32_e32 v223, v223, v213
	v_fma_f32 v223, v223, v3, v11
	v_cvt_pk_bf16_f32 v237, v222, v223
	v_lshlrev_b32_e32 v222, 16, v220
	v_sub_f32_e32 v222, v222, v205
	v_mul_f32_e32 v222, v222, v213
	v_fma_f32 v222, v222, v4, v12
	v_and_b32_e32 v223, 0xffff0000, v220
	v_sub_f32_e32 v223, v223, v205
	v_mul_f32_e32 v223, v223, v213
	v_fma_f32 v223, v223, v5, v13
	v_cvt_pk_bf16_f32 v238, v222, v223
	v_lshlrev_b32_e32 v222, 16, v221
	v_sub_f32_e32 v222, v222, v205
	v_mul_f32_e32 v222, v222, v213
	v_fma_f32 v222, v222, v6, v14
	v_and_b32_e32 v223, 0xffff0000, v221
	v_sub_f32_e32 v223, v223, v205
	v_mul_f32_e32 v223, v223, v213
	v_fma_f32 v223, v223, v7, v15
	v_cvt_pk_bf16_f32 v239, v222, v223
	ds_write_b128 v107, v[236:239] offset:1584
	v_cndmask_b32_e64 v218, v56, v52, s[6:7]
	v_cndmask_b32_e64 v219, v57, v53, s[6:7]
	v_cndmask_b32_e64 v220, v58, v54, s[6:7]
	v_cndmask_b32_e64 v221, v59, v55, s[6:7]
	v_lshlrev_b32_e32 v222, 16, v218
	v_sub_f32_e32 v222, v222, v206
	v_mul_f32_e32 v222, v222, v214
	v_fma_f32 v222, v222, v0, v8
	v_and_b32_e32 v223, 0xffff0000, v218
	v_sub_f32_e32 v223, v223, v206
	v_mul_f32_e32 v223, v223, v214
	v_fma_f32 v223, v223, v1, v9
	v_cvt_pk_bf16_f32 v232, v222, v223
	v_lshlrev_b32_e32 v222, 16, v219
	v_sub_f32_e32 v222, v222, v206
	v_mul_f32_e32 v222, v222, v214
	v_fma_f32 v222, v222, v2, v10
	v_and_b32_e32 v223, 0xffff0000, v219
	v_sub_f32_e32 v223, v223, v206
	v_mul_f32_e32 v223, v223, v214
	v_fma_f32 v223, v223, v3, v11
	v_cvt_pk_bf16_f32 v233, v222, v223
	v_lshlrev_b32_e32 v222, 16, v220
	v_sub_f32_e32 v222, v222, v206
	v_mul_f32_e32 v222, v222, v214
	v_fma_f32 v222, v222, v4, v12
	v_and_b32_e32 v223, 0xffff0000, v220
	v_sub_f32_e32 v223, v223, v206
	v_mul_f32_e32 v223, v223, v214
	v_fma_f32 v223, v223, v5, v13
	v_cvt_pk_bf16_f32 v234, v222, v223
	v_lshlrev_b32_e32 v222, 16, v221
	v_sub_f32_e32 v222, v222, v206
	v_mul_f32_e32 v222, v222, v214
	v_fma_f32 v222, v222, v6, v14
	v_and_b32_e32 v223, 0xffff0000, v221
	v_sub_f32_e32 v223, v223, v206
	v_mul_f32_e32 v223, v223, v214
	v_fma_f32 v223, v223, v7, v15
	v_cvt_pk_bf16_f32 v235, v222, v223
	ds_write_b128 v107, v[232:235] offset:2112
	v_cndmask_b32_e64 v218, v64, v60, s[6:7]
	v_cndmask_b32_e64 v219, v65, v61, s[6:7]
	v_cndmask_b32_e64 v220, v66, v62, s[6:7]
	v_cndmask_b32_e64 v221, v67, v63, s[6:7]
	v_lshlrev_b32_e32 v222, 16, v218
	v_sub_f32_e32 v222, v222, v207
	v_mul_f32_e32 v222, v222, v215
	v_fma_f32 v222, v222, v0, v8
	v_and_b32_e32 v223, 0xffff0000, v218
	v_sub_f32_e32 v223, v223, v207
	v_mul_f32_e32 v223, v223, v215
	v_fma_f32 v223, v223, v1, v9
	v_cvt_pk_bf16_f32 v236, v222, v223
	v_lshlrev_b32_e32 v222, 16, v219
	v_sub_f32_e32 v222, v222, v207
	v_mul_f32_e32 v222, v222, v215
	v_fma_f32 v222, v222, v2, v10
	v_and_b32_e32 v223, 0xffff0000, v219
	v_sub_f32_e32 v223, v223, v207
	v_mul_f32_e32 v223, v223, v215
	v_fma_f32 v223, v223, v3, v11
	v_cvt_pk_bf16_f32 v237, v222, v223
	v_lshlrev_b32_e32 v222, 16, v220
	v_sub_f32_e32 v222, v222, v207
	v_mul_f32_e32 v222, v222, v215
	v_fma_f32 v222, v222, v4, v12
	v_and_b32_e32 v223, 0xffff0000, v220
	v_sub_f32_e32 v223, v223, v207
	v_mul_f32_e32 v223, v223, v215
	v_fma_f32 v223, v223, v5, v13
	v_cvt_pk_bf16_f32 v238, v222, v223
	v_lshlrev_b32_e32 v222, 16, v221
	v_sub_f32_e32 v222, v222, v207
	v_mul_f32_e32 v222, v222, v215
	v_fma_f32 v222, v222, v6, v14
	v_and_b32_e32 v223, 0xffff0000, v221
	v_sub_f32_e32 v223, v223, v207
	v_mul_f32_e32 v223, v223, v215
	v_fma_f32 v223, v223, v7, v15
	v_cvt_pk_bf16_f32 v239, v222, v223
	ds_write_b128 v107, v[236:239] offset:2640
	v_cndmask_b32_e64 v218, v72, v68, s[6:7]
	v_cndmask_b32_e64 v219, v73, v69, s[6:7]
	v_cndmask_b32_e64 v220, v74, v70, s[6:7]
	v_cndmask_b32_e64 v221, v75, v71, s[6:7]
	v_lshlrev_b32_e32 v222, 16, v218
	v_sub_f32_e32 v222, v222, v208
	v_mul_f32_e32 v222, v222, v216
	v_fma_f32 v222, v222, v0, v8
	v_and_b32_e32 v223, 0xffff0000, v218
	v_sub_f32_e32 v223, v223, v208
	v_mul_f32_e32 v223, v223, v216
	v_fma_f32 v223, v223, v1, v9
	v_cvt_pk_bf16_f32 v232, v222, v223
	v_lshlrev_b32_e32 v222, 16, v219
	v_sub_f32_e32 v222, v222, v208
	v_mul_f32_e32 v222, v222, v216
	v_fma_f32 v222, v222, v2, v10
	v_and_b32_e32 v223, 0xffff0000, v219
	v_sub_f32_e32 v223, v223, v208
	v_mul_f32_e32 v223, v223, v216
	v_fma_f32 v223, v223, v3, v11
	v_cvt_pk_bf16_f32 v233, v222, v223
	v_lshlrev_b32_e32 v222, 16, v220
	v_sub_f32_e32 v222, v222, v208
	v_mul_f32_e32 v222, v222, v216
	v_fma_f32 v222, v222, v4, v12
	v_and_b32_e32 v223, 0xffff0000, v220
	v_sub_f32_e32 v223, v223, v208
	v_mul_f32_e32 v223, v223, v216
	v_fma_f32 v223, v223, v5, v13
	v_cvt_pk_bf16_f32 v234, v222, v223
	v_lshlrev_b32_e32 v222, 16, v221
	v_sub_f32_e32 v222, v222, v208
	v_mul_f32_e32 v222, v222, v216
	v_fma_f32 v222, v222, v6, v14
	v_and_b32_e32 v223, 0xffff0000, v221
	v_sub_f32_e32 v223, v223, v208
	v_mul_f32_e32 v223, v223, v216
	v_fma_f32 v223, v223, v7, v15
	v_cvt_pk_bf16_f32 v235, v222, v223
	ds_write_b128 v107, v[232:235] offset:3168
	v_cndmask_b32_e64 v218, v80, v76, s[6:7]
	v_cndmask_b32_e64 v219, v81, v77, s[6:7]
	v_cndmask_b32_e64 v220, v82, v78, s[6:7]
	v_cndmask_b32_e64 v221, v83, v79, s[6:7]
	v_lshlrev_b32_e32 v222, 16, v218
	v_sub_f32_e32 v222, v222, v209
	v_mul_f32_e32 v222, v222, v217
	v_fma_f32 v222, v222, v0, v8
	v_and_b32_e32 v223, 0xffff0000, v218
	v_sub_f32_e32 v223, v223, v209
	v_mul_f32_e32 v223, v223, v217
	v_fma_f32 v223, v223, v1, v9
	v_cvt_pk_bf16_f32 v236, v222, v223
	v_lshlrev_b32_e32 v222, 16, v219
	v_sub_f32_e32 v222, v222, v209
	v_mul_f32_e32 v222, v222, v217
	v_fma_f32 v222, v222, v2, v10
	v_and_b32_e32 v223, 0xffff0000, v219
	v_sub_f32_e32 v223, v223, v209
	v_mul_f32_e32 v223, v223, v217
	v_fma_f32 v223, v223, v3, v11
	v_cvt_pk_bf16_f32 v237, v222, v223
	v_lshlrev_b32_e32 v222, 16, v220
	v_sub_f32_e32 v222, v222, v209
	v_mul_f32_e32 v222, v222, v217
	v_fma_f32 v222, v222, v4, v12
	v_and_b32_e32 v223, 0xffff0000, v220
	v_sub_f32_e32 v223, v223, v209
	v_mul_f32_e32 v223, v223, v217
	v_fma_f32 v223, v223, v5, v13
	v_cvt_pk_bf16_f32 v238, v222, v223
	v_lshlrev_b32_e32 v222, 16, v221
	v_sub_f32_e32 v222, v222, v209
	v_mul_f32_e32 v222, v222, v217
	v_fma_f32 v222, v222, v6, v14
	v_and_b32_e32 v223, 0xffff0000, v221
	v_sub_f32_e32 v223, v223, v209
	v_mul_f32_e32 v223, v223, v217
	v_fma_f32 v223, v223, v7, v15
	v_cvt_pk_bf16_f32 v239, v222, v223
	ds_write_b128 v107, v[236:239] offset:3696
	s_or_b64 exec, exec, s[56:57]
	s_waitcnt vmcnt(0)
	v_mov_b32_e32 v186, 0
	v_lshlrev_b32_e32 v218, 16, v84
	v_lshlrev_b32_e32 v219, 16, v88
	v_add_f32_e32 v218, v218, v219
	v_add_f32_e32 v186, v186, v218
	v_and_b32_e32 v220, 0xffff0000, v84
	v_and_b32_e32 v221, 0xffff0000, v88
	v_add_f32_e32 v220, v220, v221
	v_add_f32_e32 v186, v186, v220
	v_lshlrev_b32_e32 v218, 16, v85
	v_lshlrev_b32_e32 v219, 16, v89
	v_add_f32_e32 v218, v218, v219
	v_add_f32_e32 v186, v186, v218
	v_and_b32_e32 v220, 0xffff0000, v85
	v_and_b32_e32 v221, 0xffff0000, v89
	v_add_f32_e32 v220, v220, v221
	v_add_f32_e32 v186, v186, v220
	v_lshlrev_b32_e32 v218, 16, v86
	v_lshlrev_b32_e32 v219, 16, v90
	v_add_f32_e32 v218, v218, v219
	v_add_f32_e32 v186, v186, v218
	v_and_b32_e32 v220, 0xffff0000, v86
	v_and_b32_e32 v221, 0xffff0000, v90
	v_add_f32_e32 v220, v220, v221
	v_add_f32_e32 v186, v186, v220
	v_lshlrev_b32_e32 v218, 16, v87
	v_lshlrev_b32_e32 v219, 16, v91
	v_add_f32_e32 v218, v218, v219
	v_add_f32_e32 v186, v186, v218
	v_and_b32_e32 v220, 0xffff0000, v87
	v_and_b32_e32 v221, 0xffff0000, v91
	v_add_f32_e32 v220, v220, v221
	v_add_f32_e32 v186, v186, v220
	v_mov_b32_e32 v187, 0
	v_lshlrev_b32_e32 v218, 16, v92
	v_lshlrev_b32_e32 v219, 16, v110
	v_add_f32_e32 v218, v218, v219
	v_add_f32_e32 v187, v187, v218
	v_and_b32_e32 v220, 0xffff0000, v92
	v_and_b32_e32 v221, 0xffff0000, v110
	v_add_f32_e32 v220, v220, v221
	v_add_f32_e32 v187, v187, v220
	v_lshlrev_b32_e32 v218, 16, v93
	v_lshlrev_b32_e32 v219, 16, v111
	v_add_f32_e32 v218, v218, v219
	v_add_f32_e32 v187, v187, v218
	v_and_b32_e32 v220, 0xffff0000, v93
	v_and_b32_e32 v221, 0xffff0000, v111
	v_add_f32_e32 v220, v220, v221
	v_add_f32_e32 v187, v187, v220
	v_lshlrev_b32_e32 v218, 16, v94
	v_lshlrev_b32_e32 v219, 16, v112
	v_add_f32_e32 v218, v218, v219
	v_add_f32_e32 v187, v187, v218
	v_and_b32_e32 v220, 0xffff0000, v94
	v_and_b32_e32 v221, 0xffff0000, v112
	v_add_f32_e32 v220, v220, v221
	v_add_f32_e32 v187, v187, v220
	v_lshlrev_b32_e32 v218, 16, v95
	v_lshlrev_b32_e32 v219, 16, v113
	v_add_f32_e32 v218, v218, v219
	v_add_f32_e32 v187, v187, v218
	v_and_b32_e32 v220, 0xffff0000, v95
	v_and_b32_e32 v221, 0xffff0000, v113
	v_add_f32_e32 v220, v220, v221
	v_add_f32_e32 v187, v187, v220
	v_mov_b32_e32 v188, 0
	v_lshlrev_b32_e32 v218, 16, v114
	v_lshlrev_b32_e32 v219, 16, v118
	v_add_f32_e32 v218, v218, v219
	v_add_f32_e32 v188, v188, v218
	v_and_b32_e32 v220, 0xffff0000, v114
	v_and_b32_e32 v221, 0xffff0000, v118
	v_add_f32_e32 v220, v220, v221
	v_add_f32_e32 v188, v188, v220
	v_lshlrev_b32_e32 v218, 16, v115
	v_lshlrev_b32_e32 v219, 16, v119
	v_add_f32_e32 v218, v218, v219
	v_add_f32_e32 v188, v188, v218
	v_and_b32_e32 v220, 0xffff0000, v115
	v_and_b32_e32 v221, 0xffff0000, v119
	v_add_f32_e32 v220, v220, v221
	v_add_f32_e32 v188, v188, v220
	v_lshlrev_b32_e32 v218, 16, v116
	v_lshlrev_b32_e32 v219, 16, v120
	v_add_f32_e32 v218, v218, v219
	v_add_f32_e32 v188, v188, v218
	v_and_b32_e32 v220, 0xffff0000, v116
	v_and_b32_e32 v221, 0xffff0000, v120
	v_add_f32_e32 v220, v220, v221
	v_add_f32_e32 v188, v188, v220
	v_lshlrev_b32_e32 v218, 16, v117
	v_lshlrev_b32_e32 v219, 16, v121
	v_add_f32_e32 v218, v218, v219
	v_add_f32_e32 v188, v188, v218
	v_and_b32_e32 v220, 0xffff0000, v117
	v_and_b32_e32 v221, 0xffff0000, v121
	v_add_f32_e32 v220, v220, v221
	v_add_f32_e32 v188, v188, v220
	v_mov_b32_e32 v189, 0
	v_lshlrev_b32_e32 v218, 16, v122
	v_lshlrev_b32_e32 v219, 16, v148
	v_add_f32_e32 v218, v218, v219
	v_add_f32_e32 v189, v189, v218
	v_and_b32_e32 v220, 0xffff0000, v122
	v_and_b32_e32 v221, 0xffff0000, v148
	v_add_f32_e32 v220, v220, v221
	v_add_f32_e32 v189, v189, v220
	v_lshlrev_b32_e32 v218, 16, v123
	v_lshlrev_b32_e32 v219, 16, v149
	v_add_f32_e32 v218, v218, v219
	v_add_f32_e32 v189, v189, v218
	v_and_b32_e32 v220, 0xffff0000, v123
	v_and_b32_e32 v221, 0xffff0000, v149
	v_add_f32_e32 v220, v220, v221
	v_add_f32_e32 v189, v189, v220
	v_lshlrev_b32_e32 v218, 16, v124
	v_lshlrev_b32_e32 v219, 16, v150
	v_add_f32_e32 v218, v218, v219
	v_add_f32_e32 v189, v189, v218
	v_and_b32_e32 v220, 0xffff0000, v124
	v_and_b32_e32 v221, 0xffff0000, v150
	v_add_f32_e32 v220, v220, v221
	v_add_f32_e32 v189, v189, v220
	v_lshlrev_b32_e32 v218, 16, v125
	v_lshlrev_b32_e32 v219, 16, v151
	v_add_f32_e32 v218, v218, v219
	v_add_f32_e32 v189, v189, v218
	v_and_b32_e32 v220, 0xffff0000, v125
	v_and_b32_e32 v221, 0xffff0000, v151
	v_add_f32_e32 v220, v220, v221
	v_add_f32_e32 v189, v189, v220
	v_mov_b32_e32 v190, 0
	v_lshlrev_b32_e32 v218, 16, v152
	v_lshlrev_b32_e32 v219, 16, v156
	v_add_f32_e32 v218, v218, v219
	v_add_f32_e32 v190, v190, v218
	v_and_b32_e32 v220, 0xffff0000, v152
	v_and_b32_e32 v221, 0xffff0000, v156
	v_add_f32_e32 v220, v220, v221
	v_add_f32_e32 v190, v190, v220
	v_lshlrev_b32_e32 v218, 16, v153
	v_lshlrev_b32_e32 v219, 16, v157
	v_add_f32_e32 v218, v218, v219
	v_add_f32_e32 v190, v190, v218
	v_and_b32_e32 v220, 0xffff0000, v153
	v_and_b32_e32 v221, 0xffff0000, v157
	v_add_f32_e32 v220, v220, v221
	v_add_f32_e32 v190, v190, v220
	v_lshlrev_b32_e32 v218, 16, v154
	v_lshlrev_b32_e32 v219, 16, v158
	v_add_f32_e32 v218, v218, v219
	v_add_f32_e32 v190, v190, v218
	v_and_b32_e32 v220, 0xffff0000, v154
	v_and_b32_e32 v221, 0xffff0000, v158
	v_add_f32_e32 v220, v220, v221
	v_add_f32_e32 v190, v190, v220
	v_lshlrev_b32_e32 v218, 16, v155
	v_lshlrev_b32_e32 v219, 16, v159
	v_add_f32_e32 v218, v218, v219
	v_add_f32_e32 v190, v190, v218
	v_and_b32_e32 v220, 0xffff0000, v155
	v_and_b32_e32 v221, 0xffff0000, v159
	v_add_f32_e32 v220, v220, v221
	v_add_f32_e32 v190, v190, v220
	v_mov_b32_e32 v191, 0
	v_lshlrev_b32_e32 v218, 16, v160
	v_lshlrev_b32_e32 v219, 16, v166
	v_add_f32_e32 v218, v218, v219
	v_add_f32_e32 v191, v191, v218
	v_and_b32_e32 v220, 0xffff0000, v160
	v_and_b32_e32 v221, 0xffff0000, v166
	v_add_f32_e32 v220, v220, v221
	v_add_f32_e32 v191, v191, v220
	v_lshlrev_b32_e32 v218, 16, v161
	v_lshlrev_b32_e32 v219, 16, v167
	v_add_f32_e32 v218, v218, v219
	v_add_f32_e32 v191, v191, v218
	v_and_b32_e32 v220, 0xffff0000, v161
	v_and_b32_e32 v221, 0xffff0000, v167
	v_add_f32_e32 v220, v220, v221
	v_add_f32_e32 v191, v191, v220
	v_lshlrev_b32_e32 v218, 16, v162
	v_lshlrev_b32_e32 v219, 16, v168
	v_add_f32_e32 v218, v218, v219
	v_add_f32_e32 v191, v191, v218
	v_and_b32_e32 v220, 0xffff0000, v162
	v_and_b32_e32 v221, 0xffff0000, v168
	v_add_f32_e32 v220, v220, v221
	v_add_f32_e32 v191, v191, v220
	v_lshlrev_b32_e32 v218, 16, v163
	v_lshlrev_b32_e32 v219, 16, v169
	v_add_f32_e32 v218, v218, v219
	v_add_f32_e32 v191, v191, v218
	v_and_b32_e32 v220, 0xffff0000, v163
	v_and_b32_e32 v221, 0xffff0000, v169
	v_add_f32_e32 v220, v220, v221
	v_add_f32_e32 v191, v191, v220
	v_mov_b32_e32 v192, 0
	v_lshlrev_b32_e32 v218, 16, v170
	v_lshlrev_b32_e32 v219, 16, v174
	v_add_f32_e32 v218, v218, v219
	v_add_f32_e32 v192, v192, v218
	v_and_b32_e32 v220, 0xffff0000, v170
	v_and_b32_e32 v221, 0xffff0000, v174
	v_add_f32_e32 v220, v220, v221
	v_add_f32_e32 v192, v192, v220
	v_lshlrev_b32_e32 v218, 16, v171
	v_lshlrev_b32_e32 v219, 16, v175
	v_add_f32_e32 v218, v218, v219
	v_add_f32_e32 v192, v192, v218
	v_and_b32_e32 v220, 0xffff0000, v171
	v_and_b32_e32 v221, 0xffff0000, v175
	v_add_f32_e32 v220, v220, v221
	v_add_f32_e32 v192, v192, v220
	v_lshlrev_b32_e32 v218, 16, v172
	v_lshlrev_b32_e32 v219, 16, v176
	v_add_f32_e32 v218, v218, v219
	v_add_f32_e32 v192, v192, v218
	v_and_b32_e32 v220, 0xffff0000, v172
	v_and_b32_e32 v221, 0xffff0000, v176
	v_add_f32_e32 v220, v220, v221
	v_add_f32_e32 v192, v192, v220
	v_lshlrev_b32_e32 v218, 16, v173
	v_lshlrev_b32_e32 v219, 16, v177
	v_add_f32_e32 v218, v218, v219
	v_add_f32_e32 v192, v192, v218
	v_and_b32_e32 v220, 0xffff0000, v173
	v_and_b32_e32 v221, 0xffff0000, v177
	v_add_f32_e32 v220, v220, v221
	v_add_f32_e32 v192, v192, v220
	v_mov_b32_e32 v193, 0
	v_lshlrev_b32_e32 v218, 16, v178
	v_lshlrev_b32_e32 v219, 16, v182
	v_add_f32_e32 v218, v218, v219
	v_add_f32_e32 v193, v193, v218
	v_and_b32_e32 v220, 0xffff0000, v178
	v_and_b32_e32 v221, 0xffff0000, v182
	v_add_f32_e32 v220, v220, v221
	v_add_f32_e32 v193, v193, v220
	v_lshlrev_b32_e32 v218, 16, v179
	v_lshlrev_b32_e32 v219, 16, v183
	v_add_f32_e32 v218, v218, v219
	v_add_f32_e32 v193, v193, v218
	v_and_b32_e32 v220, 0xffff0000, v179
	v_and_b32_e32 v221, 0xffff0000, v183
	v_add_f32_e32 v220, v220, v221
	v_add_f32_e32 v193, v193, v220
	v_lshlrev_b32_e32 v218, 16, v180
	v_lshlrev_b32_e32 v219, 16, v184
	v_add_f32_e32 v218, v218, v219
	v_add_f32_e32 v193, v193, v218
	v_and_b32_e32 v220, 0xffff0000, v180
	v_and_b32_e32 v221, 0xffff0000, v184
	v_add_f32_e32 v220, v220, v221
	v_add_f32_e32 v193, v193, v220
	v_lshlrev_b32_e32 v218, 16, v181
	v_lshlrev_b32_e32 v219, 16, v185
	v_add_f32_e32 v218, v218, v219
	v_add_f32_e32 v193, v193, v218
	v_and_b32_e32 v220, 0xffff0000, v181
	v_and_b32_e32 v221, 0xffff0000, v185
	v_add_f32_e32 v220, v220, v221
	v_add_f32_e32 v193, v193, v220
	v_xor_b32_e32 v229, 4, v228
	ds_bpermute_b32 v194, v229, v186
	ds_bpermute_b32 v195, v229, v187
	ds_bpermute_b32 v196, v229, v188
	ds_bpermute_b32 v197, v229, v189
	ds_bpermute_b32 v198, v229, v190
	ds_bpermute_b32 v199, v229, v191
	ds_bpermute_b32 v200, v229, v192
	ds_bpermute_b32 v201, v229, v193
	s_waitcnt lgkmcnt(0)
	v_add_f32_e32 v186, v186, v194
	v_add_f32_e32 v187, v187, v195
	v_add_f32_e32 v188, v188, v196
	v_add_f32_e32 v189, v189, v197
	v_add_f32_e32 v190, v190, v198
	v_add_f32_e32 v191, v191, v199
	v_add_f32_e32 v192, v192, v200
	v_add_f32_e32 v193, v193, v201
	v_xor_b32_e32 v229, 8, v228
	ds_bpermute_b32 v194, v229, v186
	ds_bpermute_b32 v195, v229, v187
	ds_bpermute_b32 v196, v229, v188
	ds_bpermute_b32 v197, v229, v189
	ds_bpermute_b32 v198, v229, v190
	ds_bpermute_b32 v199, v229, v191
	ds_bpermute_b32 v200, v229, v192
	ds_bpermute_b32 v201, v229, v193
	s_waitcnt lgkmcnt(0)
	v_add_f32_e32 v186, v186, v194
	v_add_f32_e32 v187, v187, v195
	v_add_f32_e32 v188, v188, v196
	v_add_f32_e32 v189, v189, v197
	v_add_f32_e32 v190, v190, v198
	v_add_f32_e32 v191, v191, v199
	v_add_f32_e32 v192, v192, v200
	v_add_f32_e32 v193, v193, v201
	v_xor_b32_e32 v229, 16, v228
	ds_bpermute_b32 v194, v229, v186
	ds_bpermute_b32 v195, v229, v187
	ds_bpermute_b32 v196, v229, v188
	ds_bpermute_b32 v197, v229, v189
	ds_bpermute_b32 v198, v229, v190
	ds_bpermute_b32 v199, v229, v191
	ds_bpermute_b32 v200, v229, v192
	ds_bpermute_b32 v201, v229, v193
	s_waitcnt lgkmcnt(0)
	v_add_f32_e32 v186, v186, v194
	v_add_f32_e32 v187, v187, v195
	v_add_f32_e32 v188, v188, v196
	v_add_f32_e32 v189, v189, v197
	v_add_f32_e32 v190, v190, v198
	v_add_f32_e32 v191, v191, v199
	v_add_f32_e32 v192, v192, v200
	v_add_f32_e32 v193, v193, v201
	v_xor_b32_e32 v229, 32, v228
	ds_bpermute_b32 v194, v229, v186
	ds_bpermute_b32 v195, v229, v187
	ds_bpermute_b32 v196, v229, v188
	ds_bpermute_b32 v197, v229, v189
	ds_bpermute_b32 v198, v229, v190
	ds_bpermute_b32 v199, v229, v191
	ds_bpermute_b32 v200, v229, v192
	ds_bpermute_b32 v201, v229, v193
	s_waitcnt lgkmcnt(0)
	v_add_f32_e32 v186, v186, v194
	v_add_f32_e32 v187, v187, v195
	v_add_f32_e32 v188, v188, v196
	v_add_f32_e32 v189, v189, v197
	v_add_f32_e32 v190, v190, v198
	v_add_f32_e32 v191, v191, v199
	v_add_f32_e32 v192, v192, v200
	v_add_f32_e32 v193, v193, v201
	v_xor_b32_e32 v229, 64, v228
	ds_bpermute_b32 v194, v229, v186
	ds_bpermute_b32 v195, v229, v187
	ds_bpermute_b32 v196, v229, v188
	ds_bpermute_b32 v197, v229, v189
	ds_bpermute_b32 v198, v229, v190
	ds_bpermute_b32 v199, v229, v191
	ds_bpermute_b32 v200, v229, v192
	ds_bpermute_b32 v201, v229, v193
	s_waitcnt lgkmcnt(0)
	v_add_f32_e32 v186, v186, v194
	v_add_f32_e32 v187, v187, v195
	v_add_f32_e32 v188, v188, v196
	v_add_f32_e32 v189, v189, v197
	v_add_f32_e32 v190, v190, v198
	v_add_f32_e32 v191, v191, v199
	v_add_f32_e32 v192, v192, v200
	v_add_f32_e32 v193, v193, v201
	v_xor_b32_e32 v229, 128, v228
	ds_bpermute_b32 v194, v229, v186
	ds_bpermute_b32 v195, v229, v187
	ds_bpermute_b32 v196, v229, v188
	ds_bpermute_b32 v197, v229, v189
	ds_bpermute_b32 v198, v229, v190
	ds_bpermute_b32 v199, v229, v191
	ds_bpermute_b32 v200, v229, v192
	ds_bpermute_b32 v201, v229, v193
	s_waitcnt lgkmcnt(0)
	v_add_f32_e32 v186, v186, v194
	v_add_f32_e32 v187, v187, v195
	v_add_f32_e32 v188, v188, v196
	v_add_f32_e32 v189, v189, v197
	v_add_f32_e32 v190, v190, v198
	v_add_f32_e32 v191, v191, v199
	v_add_f32_e32 v192, v192, v200
	v_add_f32_e32 v193, v193, v201
	v_mov_b32_e32 v225, 0x3a800000
	v_mul_f32_e32 v202, v186, v225
	v_mul_f32_e32 v203, v187, v225
	v_mul_f32_e32 v204, v188, v225
	v_mul_f32_e32 v205, v189, v225
	v_mul_f32_e32 v206, v190, v225
	v_mul_f32_e32 v207, v191, v225
	v_mul_f32_e32 v208, v192, v225
	v_mul_f32_e32 v209, v193, v225
	v_mov_b32_e32 v186, 0
	v_lshlrev_b32_e32 v218, 16, v84
	v_lshlrev_b32_e32 v219, 16, v88
	v_sub_f32_e32 v218, v218, v202
	v_sub_f32_e32 v219, v219, v202
	v_mul_f32_e32 v219, v219, v219
	v_fma_f32 v219, v218, v218, v219
	v_add_f32_e32 v186, v186, v219
	v_and_b32_e32 v218, 0xffff0000, v84
	v_and_b32_e32 v219, 0xffff0000, v88
	v_sub_f32_e32 v218, v218, v202
	v_sub_f32_e32 v219, v219, v202
	v_mul_f32_e32 v219, v219, v219
	v_fma_f32 v219, v218, v218, v219
	v_add_f32_e32 v186, v186, v219
	v_lshlrev_b32_e32 v218, 16, v85
	v_lshlrev_b32_e32 v219, 16, v89
	v_sub_f32_e32 v218, v218, v202
	v_sub_f32_e32 v219, v219, v202
	v_mul_f32_e32 v219, v219, v219
	v_fma_f32 v219, v218, v218, v219
	v_add_f32_e32 v186, v186, v219
	v_and_b32_e32 v218, 0xffff0000, v85
	v_and_b32_e32 v219, 0xffff0000, v89
	v_sub_f32_e32 v218, v218, v202
	v_sub_f32_e32 v219, v219, v202
	v_mul_f32_e32 v219, v219, v219
	v_fma_f32 v219, v218, v218, v219
	v_add_f32_e32 v186, v186, v219
	v_lshlrev_b32_e32 v218, 16, v86
	v_lshlrev_b32_e32 v219, 16, v90
	v_sub_f32_e32 v218, v218, v202
	v_sub_f32_e32 v219, v219, v202
	v_mul_f32_e32 v219, v219, v219
	v_fma_f32 v219, v218, v218, v219
	v_add_f32_e32 v186, v186, v219
	v_and_b32_e32 v218, 0xffff0000, v86
	v_and_b32_e32 v219, 0xffff0000, v90
	v_sub_f32_e32 v218, v218, v202
	v_sub_f32_e32 v219, v219, v202
	v_mul_f32_e32 v219, v219, v219
	v_fma_f32 v219, v218, v218, v219
	v_add_f32_e32 v186, v186, v219
	v_lshlrev_b32_e32 v218, 16, v87
	v_lshlrev_b32_e32 v219, 16, v91
	v_sub_f32_e32 v218, v218, v202
	v_sub_f32_e32 v219, v219, v202
	v_mul_f32_e32 v219, v219, v219
	v_fma_f32 v219, v218, v218, v219
	v_add_f32_e32 v186, v186, v219
	v_and_b32_e32 v218, 0xffff0000, v87
	v_and_b32_e32 v219, 0xffff0000, v91
	v_sub_f32_e32 v218, v218, v202
	v_sub_f32_e32 v219, v219, v202
	v_mul_f32_e32 v219, v219, v219
	v_fma_f32 v219, v218, v218, v219
	v_add_f32_e32 v186, v186, v219
	v_mov_b32_e32 v187, 0
	v_lshlrev_b32_e32 v218, 16, v92
	v_lshlrev_b32_e32 v219, 16, v110
	v_sub_f32_e32 v218, v218, v203
	v_sub_f32_e32 v219, v219, v203
	v_mul_f32_e32 v219, v219, v219
	v_fma_f32 v219, v218, v218, v219
	v_add_f32_e32 v187, v187, v219
	v_and_b32_e32 v218, 0xffff0000, v92
	v_and_b32_e32 v219, 0xffff0000, v110
	v_sub_f32_e32 v218, v218, v203
	v_sub_f32_e32 v219, v219, v203
	v_mul_f32_e32 v219, v219, v219
	v_fma_f32 v219, v218, v218, v219
	v_add_f32_e32 v187, v187, v219
	v_lshlrev_b32_e32 v218, 16, v93
	v_lshlrev_b32_e32 v219, 16, v111
	v_sub_f32_e32 v218, v218, v203
	v_sub_f32_e32 v219, v219, v203
	v_mul_f32_e32 v219, v219, v219
	v_fma_f32 v219, v218, v218, v219
	v_add_f32_e32 v187, v187, v219
	v_and_b32_e32 v218, 0xffff0000, v93
	v_and_b32_e32 v219, 0xffff0000, v111
	v_sub_f32_e32 v218, v218, v203
	v_sub_f32_e32 v219, v219, v203
	v_mul_f32_e32 v219, v219, v219
	v_fma_f32 v219, v218, v218, v219
	v_add_f32_e32 v187, v187, v219
	v_lshlrev_b32_e32 v218, 16, v94
	v_lshlrev_b32_e32 v219, 16, v112
	v_sub_f32_e32 v218, v218, v203
	v_sub_f32_e32 v219, v219, v203
	v_mul_f32_e32 v219, v219, v219
	v_fma_f32 v219, v218, v218, v219
	v_add_f32_e32 v187, v187, v219
	v_and_b32_e32 v218, 0xffff0000, v94
	v_and_b32_e32 v219, 0xffff0000, v112
	v_sub_f32_e32 v218, v218, v203
	v_sub_f32_e32 v219, v219, v203
	v_mul_f32_e32 v219, v219, v219
	v_fma_f32 v219, v218, v218, v219
	v_add_f32_e32 v187, v187, v219
	v_lshlrev_b32_e32 v218, 16, v95
	v_lshlrev_b32_e32 v219, 16, v113
	v_sub_f32_e32 v218, v218, v203
	v_sub_f32_e32 v219, v219, v203
	v_mul_f32_e32 v219, v219, v219
	v_fma_f32 v219, v218, v218, v219
	v_add_f32_e32 v187, v187, v219
	v_and_b32_e32 v218, 0xffff0000, v95
	v_and_b32_e32 v219, 0xffff0000, v113
	v_sub_f32_e32 v218, v218, v203
	v_sub_f32_e32 v219, v219, v203
	v_mul_f32_e32 v219, v219, v219
	v_fma_f32 v219, v218, v218, v219
	v_add_f32_e32 v187, v187, v219
	v_mov_b32_e32 v188, 0
	v_lshlrev_b32_e32 v218, 16, v114
	v_lshlrev_b32_e32 v219, 16, v118
	v_sub_f32_e32 v218, v218, v204
	v_sub_f32_e32 v219, v219, v204
	v_mul_f32_e32 v219, v219, v219
	v_fma_f32 v219, v218, v218, v219
	v_add_f32_e32 v188, v188, v219
	v_and_b32_e32 v218, 0xffff0000, v114
	v_and_b32_e32 v219, 0xffff0000, v118
	v_sub_f32_e32 v218, v218, v204
	v_sub_f32_e32 v219, v219, v204
	v_mul_f32_e32 v219, v219, v219
	v_fma_f32 v219, v218, v218, v219
	v_add_f32_e32 v188, v188, v219
	v_lshlrev_b32_e32 v218, 16, v115
	v_lshlrev_b32_e32 v219, 16, v119
	v_sub_f32_e32 v218, v218, v204
	v_sub_f32_e32 v219, v219, v204
	v_mul_f32_e32 v219, v219, v219
	v_fma_f32 v219, v218, v218, v219
	v_add_f32_e32 v188, v188, v219
	v_and_b32_e32 v218, 0xffff0000, v115
	v_and_b32_e32 v219, 0xffff0000, v119
	v_sub_f32_e32 v218, v218, v204
	v_sub_f32_e32 v219, v219, v204
	v_mul_f32_e32 v219, v219, v219
	v_fma_f32 v219, v218, v218, v219
	v_add_f32_e32 v188, v188, v219
	v_lshlrev_b32_e32 v218, 16, v116
	v_lshlrev_b32_e32 v219, 16, v120
	v_sub_f32_e32 v218, v218, v204
	v_sub_f32_e32 v219, v219, v204
	v_mul_f32_e32 v219, v219, v219
	v_fma_f32 v219, v218, v218, v219
	v_add_f32_e32 v188, v188, v219
	v_and_b32_e32 v218, 0xffff0000, v116
	v_and_b32_e32 v219, 0xffff0000, v120
	v_sub_f32_e32 v218, v218, v204
	v_sub_f32_e32 v219, v219, v204
	v_mul_f32_e32 v219, v219, v219
	v_fma_f32 v219, v218, v218, v219
	v_add_f32_e32 v188, v188, v219
	v_lshlrev_b32_e32 v218, 16, v117
	v_lshlrev_b32_e32 v219, 16, v121
	v_sub_f32_e32 v218, v218, v204
	v_sub_f32_e32 v219, v219, v204
	v_mul_f32_e32 v219, v219, v219
	v_fma_f32 v219, v218, v218, v219
	v_add_f32_e32 v188, v188, v219
	v_and_b32_e32 v218, 0xffff0000, v117
	v_and_b32_e32 v219, 0xffff0000, v121
	v_sub_f32_e32 v218, v218, v204
	v_sub_f32_e32 v219, v219, v204
	v_mul_f32_e32 v219, v219, v219
	v_fma_f32 v219, v218, v218, v219
	v_add_f32_e32 v188, v188, v219
	v_mov_b32_e32 v189, 0
	v_lshlrev_b32_e32 v218, 16, v122
	v_lshlrev_b32_e32 v219, 16, v148
	v_sub_f32_e32 v218, v218, v205
	v_sub_f32_e32 v219, v219, v205
	v_mul_f32_e32 v219, v219, v219
	v_fma_f32 v219, v218, v218, v219
	v_add_f32_e32 v189, v189, v219
	v_and_b32_e32 v218, 0xffff0000, v122
	v_and_b32_e32 v219, 0xffff0000, v148
	v_sub_f32_e32 v218, v218, v205
	v_sub_f32_e32 v219, v219, v205
	v_mul_f32_e32 v219, v219, v219
	v_fma_f32 v219, v218, v218, v219
	v_add_f32_e32 v189, v189, v219
	v_lshlrev_b32_e32 v218, 16, v123
	v_lshlrev_b32_e32 v219, 16, v149
	v_sub_f32_e32 v218, v218, v205
	v_sub_f32_e32 v219, v219, v205
	v_mul_f32_e32 v219, v219, v219
	v_fma_f32 v219, v218, v218, v219
	v_add_f32_e32 v189, v189, v219
	v_and_b32_e32 v218, 0xffff0000, v123
	v_and_b32_e32 v219, 0xffff0000, v149
	v_sub_f32_e32 v218, v218, v205
	v_sub_f32_e32 v219, v219, v205
	v_mul_f32_e32 v219, v219, v219
	v_fma_f32 v219, v218, v218, v219
	v_add_f32_e32 v189, v189, v219
	v_lshlrev_b32_e32 v218, 16, v124
	v_lshlrev_b32_e32 v219, 16, v150
	v_sub_f32_e32 v218, v218, v205
	v_sub_f32_e32 v219, v219, v205
	v_mul_f32_e32 v219, v219, v219
	v_fma_f32 v219, v218, v218, v219
	v_add_f32_e32 v189, v189, v219
	v_and_b32_e32 v218, 0xffff0000, v124
	v_and_b32_e32 v219, 0xffff0000, v150
	v_sub_f32_e32 v218, v218, v205
	v_sub_f32_e32 v219, v219, v205
	v_mul_f32_e32 v219, v219, v219
	v_fma_f32 v219, v218, v218, v219
	v_add_f32_e32 v189, v189, v219
	v_lshlrev_b32_e32 v218, 16, v125
	v_lshlrev_b32_e32 v219, 16, v151
	v_sub_f32_e32 v218, v218, v205
	v_sub_f32_e32 v219, v219, v205
	v_mul_f32_e32 v219, v219, v219
	v_fma_f32 v219, v218, v218, v219
	v_add_f32_e32 v189, v189, v219
	v_and_b32_e32 v218, 0xffff0000, v125
	v_and_b32_e32 v219, 0xffff0000, v151
	v_sub_f32_e32 v218, v218, v205
	v_sub_f32_e32 v219, v219, v205
	v_mul_f32_e32 v219, v219, v219
	v_fma_f32 v219, v218, v218, v219
	v_add_f32_e32 v189, v189, v219
	v_mov_b32_e32 v190, 0
	v_lshlrev_b32_e32 v218, 16, v152
	v_lshlrev_b32_e32 v219, 16, v156
	v_sub_f32_e32 v218, v218, v206
	v_sub_f32_e32 v219, v219, v206
	v_mul_f32_e32 v219, v219, v219
	v_fma_f32 v219, v218, v218, v219
	v_add_f32_e32 v190, v190, v219
	v_and_b32_e32 v218, 0xffff0000, v152
	v_and_b32_e32 v219, 0xffff0000, v156
	v_sub_f32_e32 v218, v218, v206
	v_sub_f32_e32 v219, v219, v206
	v_mul_f32_e32 v219, v219, v219
	v_fma_f32 v219, v218, v218, v219
	v_add_f32_e32 v190, v190, v219
	v_lshlrev_b32_e32 v218, 16, v153
	v_lshlrev_b32_e32 v219, 16, v157
	v_sub_f32_e32 v218, v218, v206
	v_sub_f32_e32 v219, v219, v206
	v_mul_f32_e32 v219, v219, v219
	v_fma_f32 v219, v218, v218, v219
	v_add_f32_e32 v190, v190, v219
	v_and_b32_e32 v218, 0xffff0000, v153
	v_and_b32_e32 v219, 0xffff0000, v157
	v_sub_f32_e32 v218, v218, v206
	v_sub_f32_e32 v219, v219, v206
	v_mul_f32_e32 v219, v219, v219
	v_fma_f32 v219, v218, v218, v219
	v_add_f32_e32 v190, v190, v219
	v_lshlrev_b32_e32 v218, 16, v154
	v_lshlrev_b32_e32 v219, 16, v158
	v_sub_f32_e32 v218, v218, v206
	v_sub_f32_e32 v219, v219, v206
	v_mul_f32_e32 v219, v219, v219
	v_fma_f32 v219, v218, v218, v219
	v_add_f32_e32 v190, v190, v219
	v_and_b32_e32 v218, 0xffff0000, v154
	v_and_b32_e32 v219, 0xffff0000, v158
	v_sub_f32_e32 v218, v218, v206
	v_sub_f32_e32 v219, v219, v206
	v_mul_f32_e32 v219, v219, v219
	v_fma_f32 v219, v218, v218, v219
	v_add_f32_e32 v190, v190, v219
	v_lshlrev_b32_e32 v218, 16, v155
	v_lshlrev_b32_e32 v219, 16, v159
	v_sub_f32_e32 v218, v218, v206
	v_sub_f32_e32 v219, v219, v206
	v_mul_f32_e32 v219, v219, v219
	v_fma_f32 v219, v218, v218, v219
	v_add_f32_e32 v190, v190, v219
	v_and_b32_e32 v218, 0xffff0000, v155
	v_and_b32_e32 v219, 0xffff0000, v159
	v_sub_f32_e32 v218, v218, v206
	v_sub_f32_e32 v219, v219, v206
	v_mul_f32_e32 v219, v219, v219
	v_fma_f32 v219, v218, v218, v219
	v_add_f32_e32 v190, v190, v219
	v_mov_b32_e32 v191, 0
	v_lshlrev_b32_e32 v218, 16, v160
	v_lshlrev_b32_e32 v219, 16, v166
	v_sub_f32_e32 v218, v218, v207
	v_sub_f32_e32 v219, v219, v207
	v_mul_f32_e32 v219, v219, v219
	v_fma_f32 v219, v218, v218, v219
	v_add_f32_e32 v191, v191, v219
	v_and_b32_e32 v218, 0xffff0000, v160
	v_and_b32_e32 v219, 0xffff0000, v166
	v_sub_f32_e32 v218, v218, v207
	v_sub_f32_e32 v219, v219, v207
	v_mul_f32_e32 v219, v219, v219
	v_fma_f32 v219, v218, v218, v219
	v_add_f32_e32 v191, v191, v219
	v_lshlrev_b32_e32 v218, 16, v161
	v_lshlrev_b32_e32 v219, 16, v167
	v_sub_f32_e32 v218, v218, v207
	v_sub_f32_e32 v219, v219, v207
	v_mul_f32_e32 v219, v219, v219
	v_fma_f32 v219, v218, v218, v219
	v_add_f32_e32 v191, v191, v219
	v_and_b32_e32 v218, 0xffff0000, v161
	v_and_b32_e32 v219, 0xffff0000, v167
	v_sub_f32_e32 v218, v218, v207
	v_sub_f32_e32 v219, v219, v207
	v_mul_f32_e32 v219, v219, v219
	v_fma_f32 v219, v218, v218, v219
	v_add_f32_e32 v191, v191, v219
	v_lshlrev_b32_e32 v218, 16, v162
	v_lshlrev_b32_e32 v219, 16, v168
	v_sub_f32_e32 v218, v218, v207
	v_sub_f32_e32 v219, v219, v207
	v_mul_f32_e32 v219, v219, v219
	v_fma_f32 v219, v218, v218, v219
	v_add_f32_e32 v191, v191, v219
	v_and_b32_e32 v218, 0xffff0000, v162
	v_and_b32_e32 v219, 0xffff0000, v168
	v_sub_f32_e32 v218, v218, v207
	v_sub_f32_e32 v219, v219, v207
	v_mul_f32_e32 v219, v219, v219
	v_fma_f32 v219, v218, v218, v219
	v_add_f32_e32 v191, v191, v219
	v_lshlrev_b32_e32 v218, 16, v163
	v_lshlrev_b32_e32 v219, 16, v169
	v_sub_f32_e32 v218, v218, v207
	v_sub_f32_e32 v219, v219, v207
	v_mul_f32_e32 v219, v219, v219
	v_fma_f32 v219, v218, v218, v219
	v_add_f32_e32 v191, v191, v219
	v_and_b32_e32 v218, 0xffff0000, v163
	v_and_b32_e32 v219, 0xffff0000, v169
	v_sub_f32_e32 v218, v218, v207
	v_sub_f32_e32 v219, v219, v207
	v_mul_f32_e32 v219, v219, v219
	v_fma_f32 v219, v218, v218, v219
	v_add_f32_e32 v191, v191, v219
	v_mov_b32_e32 v192, 0
	v_lshlrev_b32_e32 v218, 16, v170
	v_lshlrev_b32_e32 v219, 16, v174
	v_sub_f32_e32 v218, v218, v208
	v_sub_f32_e32 v219, v219, v208
	v_mul_f32_e32 v219, v219, v219
	v_fma_f32 v219, v218, v218, v219
	v_add_f32_e32 v192, v192, v219
	v_and_b32_e32 v218, 0xffff0000, v170
	v_and_b32_e32 v219, 0xffff0000, v174
	v_sub_f32_e32 v218, v218, v208
	v_sub_f32_e32 v219, v219, v208
	v_mul_f32_e32 v219, v219, v219
	v_fma_f32 v219, v218, v218, v219
	v_add_f32_e32 v192, v192, v219
	v_lshlrev_b32_e32 v218, 16, v171
	v_lshlrev_b32_e32 v219, 16, v175
	v_sub_f32_e32 v218, v218, v208
	v_sub_f32_e32 v219, v219, v208
	v_mul_f32_e32 v219, v219, v219
	v_fma_f32 v219, v218, v218, v219
	v_add_f32_e32 v192, v192, v219
	v_and_b32_e32 v218, 0xffff0000, v171
	v_and_b32_e32 v219, 0xffff0000, v175
	v_sub_f32_e32 v218, v218, v208
	v_sub_f32_e32 v219, v219, v208
	v_mul_f32_e32 v219, v219, v219
	v_fma_f32 v219, v218, v218, v219
	v_add_f32_e32 v192, v192, v219
	v_lshlrev_b32_e32 v218, 16, v172
	v_lshlrev_b32_e32 v219, 16, v176
	v_sub_f32_e32 v218, v218, v208
	v_sub_f32_e32 v219, v219, v208
	v_mul_f32_e32 v219, v219, v219
	v_fma_f32 v219, v218, v218, v219
	v_add_f32_e32 v192, v192, v219
	v_and_b32_e32 v218, 0xffff0000, v172
	v_and_b32_e32 v219, 0xffff0000, v176
	v_sub_f32_e32 v218, v218, v208
	v_sub_f32_e32 v219, v219, v208
	v_mul_f32_e32 v219, v219, v219
	v_fma_f32 v219, v218, v218, v219
	v_add_f32_e32 v192, v192, v219
	v_lshlrev_b32_e32 v218, 16, v173
	v_lshlrev_b32_e32 v219, 16, v177
	v_sub_f32_e32 v218, v218, v208
	v_sub_f32_e32 v219, v219, v208
	v_mul_f32_e32 v219, v219, v219
	v_fma_f32 v219, v218, v218, v219
	v_add_f32_e32 v192, v192, v219
	v_and_b32_e32 v218, 0xffff0000, v173
	v_and_b32_e32 v219, 0xffff0000, v177
	v_sub_f32_e32 v218, v218, v208
	v_sub_f32_e32 v219, v219, v208
	v_mul_f32_e32 v219, v219, v219
	v_fma_f32 v219, v218, v218, v219
	v_add_f32_e32 v192, v192, v219
	v_mov_b32_e32 v193, 0
	v_lshlrev_b32_e32 v218, 16, v178
	v_lshlrev_b32_e32 v219, 16, v182
	v_sub_f32_e32 v218, v218, v209
	v_sub_f32_e32 v219, v219, v209
	v_mul_f32_e32 v219, v219, v219
	v_fma_f32 v219, v218, v218, v219
	v_add_f32_e32 v193, v193, v219
	v_and_b32_e32 v218, 0xffff0000, v178
	v_and_b32_e32 v219, 0xffff0000, v182
	v_sub_f32_e32 v218, v218, v209
	v_sub_f32_e32 v219, v219, v209
	v_mul_f32_e32 v219, v219, v219
	v_fma_f32 v219, v218, v218, v219
	v_add_f32_e32 v193, v193, v219
	v_lshlrev_b32_e32 v218, 16, v179
	v_lshlrev_b32_e32 v219, 16, v183
	v_sub_f32_e32 v218, v218, v209
	v_sub_f32_e32 v219, v219, v209
	v_mul_f32_e32 v219, v219, v219
	v_fma_f32 v219, v218, v218, v219
	v_add_f32_e32 v193, v193, v219
	v_and_b32_e32 v218, 0xffff0000, v179
	v_and_b32_e32 v219, 0xffff0000, v183
	v_sub_f32_e32 v218, v218, v209
	v_sub_f32_e32 v219, v219, v209
	v_mul_f32_e32 v219, v219, v219
	v_fma_f32 v219, v218, v218, v219
	v_add_f32_e32 v193, v193, v219
	v_lshlrev_b32_e32 v218, 16, v180
	v_lshlrev_b32_e32 v219, 16, v184
	v_sub_f32_e32 v218, v218, v209
	v_sub_f32_e32 v219, v219, v209
	v_mul_f32_e32 v219, v219, v219
	v_fma_f32 v219, v218, v218, v219
	v_add_f32_e32 v193, v193, v219
	v_and_b32_e32 v218, 0xffff0000, v180
	v_and_b32_e32 v219, 0xffff0000, v184
	v_sub_f32_e32 v218, v218, v209
	v_sub_f32_e32 v219, v219, v209
	v_mul_f32_e32 v219, v219, v219
	v_fma_f32 v219, v218, v218, v219
	v_add_f32_e32 v193, v193, v219
	v_lshlrev_b32_e32 v218, 16, v181
	v_lshlrev_b32_e32 v219, 16, v185
	v_sub_f32_e32 v218, v218, v209
	v_sub_f32_e32 v219, v219, v209
	v_mul_f32_e32 v219, v219, v219
	v_fma_f32 v219, v218, v218, v219
	v_add_f32_e32 v193, v193, v219
	v_and_b32_e32 v218, 0xffff0000, v181
	v_and_b32_e32 v219, 0xffff0000, v185
	v_sub_f32_e32 v218, v218, v209
	v_sub_f32_e32 v219, v219, v209
	v_mul_f32_e32 v219, v219, v219
	v_fma_f32 v219, v218, v218, v219
	v_add_f32_e32 v193, v193, v219
	v_xor_b32_e32 v229, 4, v228
	ds_bpermute_b32 v194, v229, v186
	ds_bpermute_b32 v195, v229, v187
	ds_bpermute_b32 v196, v229, v188
	ds_bpermute_b32 v197, v229, v189
	ds_bpermute_b32 v198, v229, v190
	ds_bpermute_b32 v199, v229, v191
	ds_bpermute_b32 v200, v229, v192
	ds_bpermute_b32 v201, v229, v193
	s_waitcnt lgkmcnt(0)
	v_add_f32_e32 v186, v186, v194
	v_add_f32_e32 v187, v187, v195
	v_add_f32_e32 v188, v188, v196
	v_add_f32_e32 v189, v189, v197
	v_add_f32_e32 v190, v190, v198
	v_add_f32_e32 v191, v191, v199
	v_add_f32_e32 v192, v192, v200
	v_add_f32_e32 v193, v193, v201
	v_xor_b32_e32 v229, 8, v228
	ds_bpermute_b32 v194, v229, v186
	ds_bpermute_b32 v195, v229, v187
	ds_bpermute_b32 v196, v229, v188
	ds_bpermute_b32 v197, v229, v189
	ds_bpermute_b32 v198, v229, v190
	ds_bpermute_b32 v199, v229, v191
	ds_bpermute_b32 v200, v229, v192
	ds_bpermute_b32 v201, v229, v193
	s_waitcnt lgkmcnt(0)
	v_add_f32_e32 v186, v186, v194
	v_add_f32_e32 v187, v187, v195
	v_add_f32_e32 v188, v188, v196
	v_add_f32_e32 v189, v189, v197
	v_add_f32_e32 v190, v190, v198
	v_add_f32_e32 v191, v191, v199
	v_add_f32_e32 v192, v192, v200
	v_add_f32_e32 v193, v193, v201
	v_xor_b32_e32 v229, 16, v228
	ds_bpermute_b32 v194, v229, v186
	ds_bpermute_b32 v195, v229, v187
	ds_bpermute_b32 v196, v229, v188
	ds_bpermute_b32 v197, v229, v189
	ds_bpermute_b32 v198, v229, v190
	ds_bpermute_b32 v199, v229, v191
	ds_bpermute_b32 v200, v229, v192
	ds_bpermute_b32 v201, v229, v193
	s_waitcnt lgkmcnt(0)
	v_add_f32_e32 v186, v186, v194
	v_add_f32_e32 v187, v187, v195
	v_add_f32_e32 v188, v188, v196
	v_add_f32_e32 v189, v189, v197
	v_add_f32_e32 v190, v190, v198
	v_add_f32_e32 v191, v191, v199
	v_add_f32_e32 v192, v192, v200
	v_add_f32_e32 v193, v193, v201
	v_xor_b32_e32 v229, 32, v228
	ds_bpermute_b32 v194, v229, v186
	ds_bpermute_b32 v195, v229, v187
	ds_bpermute_b32 v196, v229, v188
	ds_bpermute_b32 v197, v229, v189
	ds_bpermute_b32 v198, v229, v190
	ds_bpermute_b32 v199, v229, v191
	ds_bpermute_b32 v200, v229, v192
	ds_bpermute_b32 v201, v229, v193
	s_waitcnt lgkmcnt(0)
	v_add_f32_e32 v186, v186, v194
	v_add_f32_e32 v187, v187, v195
	v_add_f32_e32 v188, v188, v196
	v_add_f32_e32 v189, v189, v197
	v_add_f32_e32 v190, v190, v198
	v_add_f32_e32 v191, v191, v199
	v_add_f32_e32 v192, v192, v200
	v_add_f32_e32 v193, v193, v201
	v_xor_b32_e32 v229, 64, v228
	ds_bpermute_b32 v194, v229, v186
	ds_bpermute_b32 v195, v229, v187
	ds_bpermute_b32 v196, v229, v188
	ds_bpermute_b32 v197, v229, v189
	ds_bpermute_b32 v198, v229, v190
	ds_bpermute_b32 v199, v229, v191
	ds_bpermute_b32 v200, v229, v192
	ds_bpermute_b32 v201, v229, v193
	s_waitcnt lgkmcnt(0)
	v_add_f32_e32 v186, v186, v194
	v_add_f32_e32 v187, v187, v195
	v_add_f32_e32 v188, v188, v196
	v_add_f32_e32 v189, v189, v197
	v_add_f32_e32 v190, v190, v198
	v_add_f32_e32 v191, v191, v199
	v_add_f32_e32 v192, v192, v200
	v_add_f32_e32 v193, v193, v201
	v_xor_b32_e32 v229, 128, v228
	ds_bpermute_b32 v194, v229, v186
	ds_bpermute_b32 v195, v229, v187
	ds_bpermute_b32 v196, v229, v188
	ds_bpermute_b32 v197, v229, v189
	ds_bpermute_b32 v198, v229, v190
	ds_bpermute_b32 v199, v229, v191
	ds_bpermute_b32 v200, v229, v192
	ds_bpermute_b32 v201, v229, v193
	s_waitcnt lgkmcnt(0)
	v_add_f32_e32 v186, v186, v194
	v_add_f32_e32 v187, v187, v195
	v_add_f32_e32 v188, v188, v196
	v_add_f32_e32 v189, v189, v197
	v_add_f32_e32 v190, v190, v198
	v_add_f32_e32 v191, v191, v199
	v_add_f32_e32 v192, v192, v200
	v_add_f32_e32 v193, v193, v201
	v_mov_b32_e32 v224, 0x358637bd
	v_fma_f32 v210, v186, v225, v224
	v_rsq_f32_e32 v210, v210
	v_fma_f32 v211, v187, v225, v224
	v_rsq_f32_e32 v211, v211
	v_fma_f32 v212, v188, v225, v224
	v_rsq_f32_e32 v212, v212
	v_fma_f32 v213, v189, v225, v224
	v_rsq_f32_e32 v213, v213
	v_fma_f32 v214, v190, v225, v224
	v_rsq_f32_e32 v214, v214
	v_fma_f32 v215, v191, v225, v224
	v_rsq_f32_e32 v215, v215
	v_fma_f32 v216, v192, v225, v224
	v_rsq_f32_e32 v216, v216
	v_fma_f32 v217, v193, v225, v224
	v_rsq_f32_e32 v217, v217
	s_and_saveexec_b64 s[56:57], s[4:5]
	v_cndmask_b32_e64 v218, v88, v84, s[6:7]
	v_cndmask_b32_e64 v219, v89, v85, s[6:7]
	v_cndmask_b32_e64 v220, v90, v86, s[6:7]
	v_cndmask_b32_e64 v221, v91, v87, s[6:7]
	v_lshlrev_b32_e32 v222, 16, v218
	v_sub_f32_e32 v222, v222, v202
	v_mul_f32_e32 v222, v222, v210
	v_fma_f32 v222, v222, v0, v8
	v_and_b32_e32 v223, 0xffff0000, v218
	v_sub_f32_e32 v223, v223, v202
	v_mul_f32_e32 v223, v223, v210
	v_fma_f32 v223, v223, v1, v9
	v_cvt_pk_bf16_f32 v232, v222, v223
	v_lshlrev_b32_e32 v222, 16, v219
	v_sub_f32_e32 v222, v222, v202
	v_mul_f32_e32 v222, v222, v210
	v_fma_f32 v222, v222, v2, v10
	v_and_b32_e32 v223, 0xffff0000, v219
	v_sub_f32_e32 v223, v223, v202
	v_mul_f32_e32 v223, v223, v210
	v_fma_f32 v223, v223, v3, v11
	v_cvt_pk_bf16_f32 v233, v222, v223
	v_lshlrev_b32_e32 v222, 16, v220
	v_sub_f32_e32 v222, v222, v202
	v_mul_f32_e32 v222, v222, v210
	v_fma_f32 v222, v222, v4, v12
	v_and_b32_e32 v223, 0xffff0000, v220
	v_sub_f32_e32 v223, v223, v202
	v_mul_f32_e32 v223, v223, v210
	v_fma_f32 v223, v223, v5, v13
	v_cvt_pk_bf16_f32 v234, v222, v223
	v_lshlrev_b32_e32 v222, 16, v221
	v_sub_f32_e32 v222, v222, v202
	v_mul_f32_e32 v222, v222, v210
	v_fma_f32 v222, v222, v6, v14
	v_and_b32_e32 v223, 0xffff0000, v221
	v_sub_f32_e32 v223, v223, v202
	v_mul_f32_e32 v223, v223, v210
	v_fma_f32 v223, v223, v7, v15
	v_cvt_pk_bf16_f32 v235, v222, v223
	ds_write_b128 v107, v[232:235] offset:4224
	v_cndmask_b32_e64 v218, v110, v92, s[6:7]
	v_cndmask_b32_e64 v219, v111, v93, s[6:7]
	v_cndmask_b32_e64 v220, v112, v94, s[6:7]
	v_cndmask_b32_e64 v221, v113, v95, s[6:7]
	v_lshlrev_b32_e32 v222, 16, v218
	v_sub_f32_e32 v222, v222, v203
	v_mul_f32_e32 v222, v222, v211
	v_fma_f32 v222, v222, v0, v8
	v_and_b32_e32 v223, 0xffff0000, v218
	v_sub_f32_e32 v223, v223, v203
	v_mul_f32_e32 v223, v223, v211
	v_fma_f32 v223, v223, v1, v9
	v_cvt_pk_bf16_f32 v236, v222, v223
	v_lshlrev_b32_e32 v222, 16, v219
	v_sub_f32_e32 v222, v222, v203
	v_mul_f32_e32 v222, v222, v211
	v_fma_f32 v222, v222, v2, v10
	v_and_b32_e32 v223, 0xffff0000, v219
	v_sub_f32_e32 v223, v223, v203
	v_mul_f32_e32 v223, v223, v211
	v_fma_f32 v223, v223, v3, v11
	v_cvt_pk_bf16_f32 v237, v222, v223
	v_lshlrev_b32_e32 v222, 16, v220
	v_sub_f32_e32 v222, v222, v203
	v_mul_f32_e32 v222, v222, v211
	v_fma_f32 v222, v222, v4, v12
	v_and_b32_e32 v223, 0xffff0000, v220
	v_sub_f32_e32 v223, v223, v203
	v_mul_f32_e32 v223, v223, v211
	v_fma_f32 v223, v223, v5, v13
	v_cvt_pk_bf16_f32 v238, v222, v223
	v_lshlrev_b32_e32 v222, 16, v221
	v_sub_f32_e32 v222, v222, v203
	v_mul_f32_e32 v222, v222, v211
	v_fma_f32 v222, v222, v6, v14
	v_and_b32_e32 v223, 0xffff0000, v221
	v_sub_f32_e32 v223, v223, v203
	v_mul_f32_e32 v223, v223, v211
	v_fma_f32 v223, v223, v7, v15
	v_cvt_pk_bf16_f32 v239, v222, v223
	ds_write_b128 v107, v[236:239] offset:4752
	v_cndmask_b32_e64 v218, v118, v114, s[6:7]
	v_cndmask_b32_e64 v219, v119, v115, s[6:7]
	v_cndmask_b32_e64 v220, v120, v116, s[6:7]
	v_cndmask_b32_e64 v221, v121, v117, s[6:7]
	v_lshlrev_b32_e32 v222, 16, v218
	v_sub_f32_e32 v222, v222, v204
	v_mul_f32_e32 v222, v222, v212
	v_fma_f32 v222, v222, v0, v8
	v_and_b32_e32 v223, 0xffff0000, v218
	v_sub_f32_e32 v223, v223, v204
	v_mul_f32_e32 v223, v223, v212
	v_fma_f32 v223, v223, v1, v9
	v_cvt_pk_bf16_f32 v232, v222, v223
	v_lshlrev_b32_e32 v222, 16, v219
	v_sub_f32_e32 v222, v222, v204
	v_mul_f32_e32 v222, v222, v212
	v_fma_f32 v222, v222, v2, v10
	v_and_b32_e32 v223, 0xffff0000, v219
	v_sub_f32_e32 v223, v223, v204
	v_mul_f32_e32 v223, v223, v212
	v_fma_f32 v223, v223, v3, v11
	v_cvt_pk_bf16_f32 v233, v222, v223
	v_lshlrev_b32_e32 v222, 16, v220
	v_sub_f32_e32 v222, v222, v204
	v_mul_f32_e32 v222, v222, v212
	v_fma_f32 v222, v222, v4, v12
	v_and_b32_e32 v223, 0xffff0000, v220
	v_sub_f32_e32 v223, v223, v204
	v_mul_f32_e32 v223, v223, v212
	v_fma_f32 v223, v223, v5, v13
	v_cvt_pk_bf16_f32 v234, v222, v223
	v_lshlrev_b32_e32 v222, 16, v221
	v_sub_f32_e32 v222, v222, v204
	v_mul_f32_e32 v222, v222, v212
	v_fma_f32 v222, v222, v6, v14
	v_and_b32_e32 v223, 0xffff0000, v221
	v_sub_f32_e32 v223, v223, v204
	v_mul_f32_e32 v223, v223, v212
	v_fma_f32 v223, v223, v7, v15
	v_cvt_pk_bf16_f32 v235, v222, v223
	ds_write_b128 v107, v[232:235] offset:5280
	v_cndmask_b32_e64 v218, v148, v122, s[6:7]
	v_cndmask_b32_e64 v219, v149, v123, s[6:7]
	v_cndmask_b32_e64 v220, v150, v124, s[6:7]
	v_cndmask_b32_e64 v221, v151, v125, s[6:7]
	v_lshlrev_b32_e32 v222, 16, v218
	v_sub_f32_e32 v222, v222, v205
	v_mul_f32_e32 v222, v222, v213
	v_fma_f32 v222, v222, v0, v8
	v_and_b32_e32 v223, 0xffff0000, v218
	v_sub_f32_e32 v223, v223, v205
	v_mul_f32_e32 v223, v223, v213
	v_fma_f32 v223, v223, v1, v9
	v_cvt_pk_bf16_f32 v236, v222, v223
	v_lshlrev_b32_e32 v222, 16, v219
	v_sub_f32_e32 v222, v222, v205
	v_mul_f32_e32 v222, v222, v213
	v_fma_f32 v222, v222, v2, v10
	v_and_b32_e32 v223, 0xffff0000, v219
	v_sub_f32_e32 v223, v223, v205
	v_mul_f32_e32 v223, v223, v213
	v_fma_f32 v223, v223, v3, v11
	v_cvt_pk_bf16_f32 v237, v222, v223
	v_lshlrev_b32_e32 v222, 16, v220
	v_sub_f32_e32 v222, v222, v205
	v_mul_f32_e32 v222, v222, v213
	v_fma_f32 v222, v222, v4, v12
	v_and_b32_e32 v223, 0xffff0000, v220
	v_sub_f32_e32 v223, v223, v205
	v_mul_f32_e32 v223, v223, v213
	v_fma_f32 v223, v223, v5, v13
	v_cvt_pk_bf16_f32 v238, v222, v223
	v_lshlrev_b32_e32 v222, 16, v221
	v_sub_f32_e32 v222, v222, v205
	v_mul_f32_e32 v222, v222, v213
	v_fma_f32 v222, v222, v6, v14
	v_and_b32_e32 v223, 0xffff0000, v221
	v_sub_f32_e32 v223, v223, v205
	v_mul_f32_e32 v223, v223, v213
	v_fma_f32 v223, v223, v7, v15
	v_cvt_pk_bf16_f32 v239, v222, v223
	ds_write_b128 v107, v[236:239] offset:5808
	v_cndmask_b32_e64 v218, v156, v152, s[6:7]
	v_cndmask_b32_e64 v219, v157, v153, s[6:7]
	v_cndmask_b32_e64 v220, v158, v154, s[6:7]
	v_cndmask_b32_e64 v221, v159, v155, s[6:7]
	v_lshlrev_b32_e32 v222, 16, v218
	v_sub_f32_e32 v222, v222, v206
	v_mul_f32_e32 v222, v222, v214
	v_fma_f32 v222, v222, v0, v8
	v_and_b32_e32 v223, 0xffff0000, v218
	v_sub_f32_e32 v223, v223, v206
	v_mul_f32_e32 v223, v223, v214
	v_fma_f32 v223, v223, v1, v9
	v_cvt_pk_bf16_f32 v232, v222, v223
	v_lshlrev_b32_e32 v222, 16, v219
	v_sub_f32_e32 v222, v222, v206
	v_mul_f32_e32 v222, v222, v214
	v_fma_f32 v222, v222, v2, v10
	v_and_b32_e32 v223, 0xffff0000, v219
	v_sub_f32_e32 v223, v223, v206
	v_mul_f32_e32 v223, v223, v214
	v_fma_f32 v223, v223, v3, v11
	v_cvt_pk_bf16_f32 v233, v222, v223
	v_lshlrev_b32_e32 v222, 16, v220
	v_sub_f32_e32 v222, v222, v206
	v_mul_f32_e32 v222, v222, v214
	v_fma_f32 v222, v222, v4, v12
	v_and_b32_e32 v223, 0xffff0000, v220
	v_sub_f32_e32 v223, v223, v206
	v_mul_f32_e32 v223, v223, v214
	v_fma_f32 v223, v223, v5, v13
	v_cvt_pk_bf16_f32 v234, v222, v223
	v_lshlrev_b32_e32 v222, 16, v221
	v_sub_f32_e32 v222, v222, v206
	v_mul_f32_e32 v222, v222, v214
	v_fma_f32 v222, v222, v6, v14
	v_and_b32_e32 v223, 0xffff0000, v221
	v_sub_f32_e32 v223, v223, v206
	v_mul_f32_e32 v223, v223, v214
	v_fma_f32 v223, v223, v7, v15
	v_cvt_pk_bf16_f32 v235, v222, v223
	ds_write_b128 v107, v[232:235] offset:6336
	v_cndmask_b32_e64 v218, v166, v160, s[6:7]
	v_cndmask_b32_e64 v219, v167, v161, s[6:7]
	v_cndmask_b32_e64 v220, v168, v162, s[6:7]
	v_cndmask_b32_e64 v221, v169, v163, s[6:7]
	v_lshlrev_b32_e32 v222, 16, v218
	v_sub_f32_e32 v222, v222, v207
	v_mul_f32_e32 v222, v222, v215
	v_fma_f32 v222, v222, v0, v8
	v_and_b32_e32 v223, 0xffff0000, v218
	v_sub_f32_e32 v223, v223, v207
	v_mul_f32_e32 v223, v223, v215
	v_fma_f32 v223, v223, v1, v9
	v_cvt_pk_bf16_f32 v236, v222, v223
	v_lshlrev_b32_e32 v222, 16, v219
	v_sub_f32_e32 v222, v222, v207
	v_mul_f32_e32 v222, v222, v215
	v_fma_f32 v222, v222, v2, v10
	v_and_b32_e32 v223, 0xffff0000, v219
	v_sub_f32_e32 v223, v223, v207
	v_mul_f32_e32 v223, v223, v215
	v_fma_f32 v223, v223, v3, v11
	v_cvt_pk_bf16_f32 v237, v222, v223
	v_lshlrev_b32_e32 v222, 16, v220
	v_sub_f32_e32 v222, v222, v207
	v_mul_f32_e32 v222, v222, v215
	v_fma_f32 v222, v222, v4, v12
	v_and_b32_e32 v223, 0xffff0000, v220
	v_sub_f32_e32 v223, v223, v207
	v_mul_f32_e32 v223, v223, v215
	v_fma_f32 v223, v223, v5, v13
	v_cvt_pk_bf16_f32 v238, v222, v223
	v_lshlrev_b32_e32 v222, 16, v221
	v_sub_f32_e32 v222, v222, v207
	v_mul_f32_e32 v222, v222, v215
	v_fma_f32 v222, v222, v6, v14
	v_and_b32_e32 v223, 0xffff0000, v221
	v_sub_f32_e32 v223, v223, v207
	v_mul_f32_e32 v223, v223, v215
	v_fma_f32 v223, v223, v7, v15
	v_cvt_pk_bf16_f32 v239, v222, v223
	ds_write_b128 v107, v[236:239] offset:6864
	v_cndmask_b32_e64 v218, v174, v170, s[6:7]
	v_cndmask_b32_e64 v219, v175, v171, s[6:7]
	v_cndmask_b32_e64 v220, v176, v172, s[6:7]
	v_cndmask_b32_e64 v221, v177, v173, s[6:7]
	v_lshlrev_b32_e32 v222, 16, v218
	v_sub_f32_e32 v222, v222, v208
	v_mul_f32_e32 v222, v222, v216
	v_fma_f32 v222, v222, v0, v8
	v_and_b32_e32 v223, 0xffff0000, v218
	v_sub_f32_e32 v223, v223, v208
	v_mul_f32_e32 v223, v223, v216
	v_fma_f32 v223, v223, v1, v9
	v_cvt_pk_bf16_f32 v232, v222, v223
	v_lshlrev_b32_e32 v222, 16, v219
	v_sub_f32_e32 v222, v222, v208
	v_mul_f32_e32 v222, v222, v216
	v_fma_f32 v222, v222, v2, v10
	v_and_b32_e32 v223, 0xffff0000, v219
	v_sub_f32_e32 v223, v223, v208
	v_mul_f32_e32 v223, v223, v216
	v_fma_f32 v223, v223, v3, v11
	v_cvt_pk_bf16_f32 v233, v222, v223
	v_lshlrev_b32_e32 v222, 16, v220
	v_sub_f32_e32 v222, v222, v208
	v_mul_f32_e32 v222, v222, v216
	v_fma_f32 v222, v222, v4, v12
	v_and_b32_e32 v223, 0xffff0000, v220
	v_sub_f32_e32 v223, v223, v208
	v_mul_f32_e32 v223, v223, v216
	v_fma_f32 v223, v223, v5, v13
	v_cvt_pk_bf16_f32 v234, v222, v223
	v_lshlrev_b32_e32 v222, 16, v221
	v_sub_f32_e32 v222, v222, v208
	v_mul_f32_e32 v222, v222, v216
	v_fma_f32 v222, v222, v6, v14
	v_and_b32_e32 v223, 0xffff0000, v221
	v_sub_f32_e32 v223, v223, v208
	v_mul_f32_e32 v223, v223, v216
	v_fma_f32 v223, v223, v7, v15
	v_cvt_pk_bf16_f32 v235, v222, v223
	ds_write_b128 v107, v[232:235] offset:7392
	v_cndmask_b32_e64 v218, v182, v178, s[6:7]
	v_cndmask_b32_e64 v219, v183, v179, s[6:7]
	v_cndmask_b32_e64 v220, v184, v180, s[6:7]
	v_cndmask_b32_e64 v221, v185, v181, s[6:7]
	v_lshlrev_b32_e32 v222, 16, v218
	v_sub_f32_e32 v222, v222, v209
	v_mul_f32_e32 v222, v222, v217
	v_fma_f32 v222, v222, v0, v8
	v_and_b32_e32 v223, 0xffff0000, v218
	v_sub_f32_e32 v223, v223, v209
	v_mul_f32_e32 v223, v223, v217
	v_fma_f32 v223, v223, v1, v9
	v_cvt_pk_bf16_f32 v236, v222, v223
	v_lshlrev_b32_e32 v222, 16, v219
	v_sub_f32_e32 v222, v222, v209
	v_mul_f32_e32 v222, v222, v217
	v_fma_f32 v222, v222, v2, v10
	v_and_b32_e32 v223, 0xffff0000, v219
	v_sub_f32_e32 v223, v223, v209
	v_mul_f32_e32 v223, v223, v217
	v_fma_f32 v223, v223, v3, v11
	v_cvt_pk_bf16_f32 v237, v222, v223
	v_lshlrev_b32_e32 v222, 16, v220
	v_sub_f32_e32 v222, v222, v209
	v_mul_f32_e32 v222, v222, v217
	v_fma_f32 v222, v222, v4, v12
	v_and_b32_e32 v223, 0xffff0000, v220
	v_sub_f32_e32 v223, v223, v209
	v_mul_f32_e32 v223, v223, v217
	v_fma_f32 v223, v223, v5, v13
	v_cvt_pk_bf16_f32 v238, v222, v223
	v_lshlrev_b32_e32 v222, 16, v221
	v_sub_f32_e32 v222, v222, v209
	v_mul_f32_e32 v222, v222, v217
	v_fma_f32 v222, v222, v6, v14
	v_and_b32_e32 v223, 0xffff0000, v221
	v_sub_f32_e32 v223, v223, v209
	v_mul_f32_e32 v223, v223, v217
	v_fma_f32 v223, v223, v7, v15
	v_cvt_pk_bf16_f32 v239, v222, v223
	ds_write_b128 v107, v[236:239] offset:7920
	s_or_b64 exec, exec, s[56:57]
	s_branch .LBB0_349
	s_branch .LBB0_347
